# P1 row pass: 8 rows unrolled with next-row prefetch; odd waves build the rotary table before their rows
# speedup vs baseline: 1.0023x; 1.0023x over previous
; __device__ __forceinline__ void rows_norm_mod(Ctx& X, const float* src, const bf16_t* delta, float* x1out, const float* w, const float* sc, const float* sh, bf16_t* dst, bool do_cs) {
;     f32x4 pa[8], pb[8];
; #pragma unroll
;     for (int j = 0; j < 8; ++j) { const int col = 4 * X.lane + 256 * j; pa[j] = *(const f32x4*)(w + col) * (*(const f32x4*)(sc + col) + 1.f); pb[j] = *(const f32x4*)(sh + col); }
;     for (int row = X.gw; row < S; row += X.NGW) {
.LBB0_100:
	s_cmp_lt_i32 s92, 2
	s_cselect_b64 s[2:3], -1, 0
	s_and_b64 s[10:11], s[2:3], s[0:1]
	s_andn2_b64 vcc, exec, s[10:11]
	s_cbranch_vccnz .LBB0_116
	s_mov_b32 s31, 0
	s_cmp_lg_u32 s94, 0x100
	s_cbranch_scc1 .Lp1_rows
	s_bitcmp1_b32 s97, 0
	s_cbranch_scc0 .Lp1_rows
	s_mov_b32 s31, 1
	s_branch .LBB0_104
.Lp1_rows:
	s_cmpk_gt_i32 s48, 0x3fff
	s_cbranch_scc1 .LBB0_104
	s_add_u32 s0, s90, 0x2000
	s_addc_u32 s1, s91, 0
	v_lshlrev_b32_e32 v44, 4, v208
	global_load_dwordx4 v[32:35], v44, s[0:1]
	v_or_b32_e32 v0, 0x400, v44
	v_or_b32_e32 v20, 0x1000, v44
	global_load_dwordx4 v[36:39], v0, s[0:1]
	global_load_dwordx4 v[50:53], v20, s[0:1]
	v_or_b32_e32 v0, 0x800, v44
	global_load_dwordx4 v[40:43], v0, s[0:1]
	v_or_b32_e32 v0, 0xc00, v44
	v_or_b32_e32 v45, 0x1400, v44
	v_or_b32_e32 v98, 0x1800, v44
	global_load_dwordx4 v[46:49], v0, s[0:1]
	global_load_dwordx4 v[54:57], v45, s[0:1]
	global_load_dwordx4 v[58:61], v98, s[0:1]
	v_or_b32_e32 v99, 0x1c00, v44
	global_load_dwordx4 v[62:65], v99, s[0:1]
	global_load_dwordx4 v[66:69], v44, s[62:63]
	global_load_dwordx4 v[70:73], v44, s[62:63] offset:1024
	global_load_dwordx4 v[74:77], v44, s[62:63] offset:2048
	global_load_dwordx4 v[78:81], v44, s[62:63] offset:3072
	global_load_dwordx4 v[82:85], v20, s[62:63]
	global_load_dwordx4 v[86:89], v45, s[62:63]
	global_load_dwordx4 v[90:93], v98, s[62:63]
	global_load_dwordx4 v[94:97], v99, s[62:63]
	v_mbcnt_lo_u32_b32 v12, -1, 0
	global_load_dwordx4 v[0:3], v44, s[90:91] offset:1024
	global_load_dwordx4 v[4:7], v44, s[90:91] offset:2048
	global_load_dwordx4 v[8:11], v44, s[90:91] offset:3072
	v_mbcnt_hi_u32_b32 v105, -1, v12
	global_load_dwordx4 v[12:15], v44, s[90:91]
	global_load_dwordx4 v[16:19], v20, s[90:91]
	s_nop 0
	global_load_dwordx4 v[20:23], v45, s[90:91]
	global_load_dwordx4 v[24:27], v98, s[90:91]
	global_load_dwordx4 v[28:31], v99, s[90:91]
	v_and_b32_e32 v100, 64, v105
	v_xor_b32_e32 v101, 1, v105
	v_add_u32_e32 v106, 64, v100
	v_xor_b32_e32 v45, 2, v105
	v_cmp_lt_i32_e32 vcc, v101, v106
	v_xor_b32_e32 v98, 4, v105
	v_xor_b32_e32 v99, 8, v105
	v_cndmask_b32_e32 v100, v105, v101, vcc
	v_cmp_lt_i32_e32 vcc, v45, v106
	v_xor_b32_e32 v104, 16, v105
	s_ashr_i32 s49, s48, 31
	v_cndmask_b32_e32 v45, v105, v45, vcc
	v_cmp_lt_i32_e32 vcc, v98, v106
	s_lshl_b64 s[0:1], s[48:49], 13
	s_add_u32 s0, s52, s0
	v_cndmask_b32_e32 v102, v105, v98, vcc
	v_cmp_lt_i32_e32 vcc, v99, v106
	v_lshlrev_b32_e32 v101, 2, v45
	v_mov_b32_e32 v45, 0
	v_cndmask_b32_e32 v103, v105, v99, vcc
	v_cmp_lt_i32_e32 vcc, v104, v106
	s_addc_u32 s1, s53, s1
	s_ashr_i32 s51, s50, 31
	s_lshl_b64 s[2:3], s[48:49], 12
	v_lshlrev_b32_e32 v100, 2, v100
	v_lshlrev_b32_e32 v102, 2, v102
	v_lshlrev_b32_e32 v103, 2, v103
	s_waitcnt vmcnt(23)
	v_pk_add_f32 v[32:33], v[32:33], 1.0 op_sel_hi:[1,0]
	v_pk_add_f32 v[34:35], v[34:35], 1.0 op_sel_hi:[1,0]
	s_waitcnt vmcnt(22)
	v_pk_add_f32 v[38:39], v[38:39], 1.0 op_sel_hi:[1,0]
	s_waitcnt vmcnt(21)
	v_pk_add_f32 v[52:53], v[52:53], 1.0 op_sel_hi:[1,0]
	v_pk_add_f32 v[36:37], v[36:37], 1.0 op_sel_hi:[1,0]
	s_waitcnt vmcnt(20)
	v_pk_add_f32 v[42:43], v[42:43], 1.0 op_sel_hi:[1,0]
	s_waitcnt vmcnt(15)
	v_pk_mul_f32 v[66:67], v[66:67], v[32:33]
	v_cndmask_b32_e32 v32, v105, v104, vcc
	v_lshlrev_b32_e32 v104, 2, v32
	v_xor_b32_e32 v32, 32, v105
	v_cmp_lt_i32_e32 vcc, v32, v106
	v_pk_add_f32 v[48:49], v[48:49], 1.0 op_sel_hi:[1,0]
	v_pk_add_f32 v[56:57], v[56:57], 1.0 op_sel_hi:[1,0]
	v_cndmask_b32_e32 v32, v105, v32, vcc
	v_pk_add_f32 v[60:61], v[60:61], 1.0 op_sel_hi:[1,0]
	v_pk_add_f32 v[98:99], v[64:65], 1.0 op_sel_hi:[1,0]
	v_lshlrev_b32_e32 v105, 2, v32
	v_lshl_add_u64 v[32:33], s[0:1], 0, v[44:45]
	s_mov_b64 s[0:1], 0x1000
	v_pk_mul_f32 v[64:65], v[68:69], v[34:35]
	s_waitcnt vmcnt(14)
	v_pk_mul_f32 v[68:69], v[72:73], v[38:39]
	s_waitcnt vmcnt(13)
	v_pk_mul_f32 v[72:73], v[76:77], v[42:43]
	s_waitcnt vmcnt(12)
	v_pk_mul_f32 v[76:77], v[80:81], v[48:49]
	s_waitcnt vmcnt(11)
	v_pk_mul_f32 v[80:81], v[84:85], v[52:53]
	s_waitcnt vmcnt(10)
	v_pk_mul_f32 v[84:85], v[88:89], v[56:57]
	s_waitcnt vmcnt(9)
	v_pk_mul_f32 v[88:89], v[92:93], v[60:61]
	s_waitcnt vmcnt(8)
	v_pk_mul_f32 v[92:93], v[96:97], v[98:99]
	v_lshl_add_u64 v[96:97], v[32:33], 0, s[0:1]
	s_lshl_b64 s[0:1], s[50:51], 13
	s_add_u32 s2, s90, s2
	v_lshlrev_b32_e32 v44, 3, v208
	s_addc_u32 s3, s91, s3
	v_pk_add_f32 v[40:41], v[40:41], 1.0 op_sel_hi:[1,0]
	v_pk_add_f32 v[46:47], v[46:47], 1.0 op_sel_hi:[1,0]
	v_pk_add_f32 v[50:51], v[50:51], 1.0 op_sel_hi:[1,0]
	v_pk_add_f32 v[54:55], v[54:55], 1.0 op_sel_hi:[1,0]
	v_pk_add_f32 v[58:59], v[58:59], 1.0 op_sel_hi:[1,0]
	v_pk_add_f32 v[62:63], v[62:63], 1.0 op_sel_hi:[1,0]
	v_lshl_add_u64 v[32:33], s[2:3], 0, v[44:45]
	s_mov_b64 s[2:3], 0x7700000
	v_pk_mul_f32 v[70:71], v[70:71], v[36:37]
	v_pk_mul_f32 v[74:75], v[74:75], v[40:41]
	v_pk_mul_f32 v[78:79], v[78:79], v[46:47]
	v_pk_mul_f32 v[82:83], v[82:83], v[50:51]
	v_pk_mul_f32 v[86:87], v[86:87], v[54:55]
	v_pk_mul_f32 v[90:91], v[90:91], v[58:59]
	v_pk_mul_f32 v[94:95], v[94:95], v[62:63]
	v_lshl_add_u64 v[98:99], v[32:33], 0, s[2:3]
	s_lshl_b64 s[4:5], s[50:51], 12
	v_mov_b32_e32 v106, 0x358637bd
	s_mov_b32 s2, 0x800000
	s_mov_b32 s3, s48
	s_cmp_lg_u32 s94, 0x100
	s_cbranch_scc1 .LBB0_103
; __device__ __forceinline__ unsigned pk2_rne(float lo, float hi) { const f32x2_t f = {lo, hi}; return __builtin_bit_cast(unsigned, __builtin_convertvector(f, bf16x2_t)); }
; __device__ __forceinline__ float bflo(unsigned w) { return __uint_as_float(w << 16); }
; __device__ __forceinline__ float bfhi(unsigned w) { return __uint_as_float(w & 0xffff0000u); }
; __device__ __forceinline__ void rows_norm_mod(Ctx& X, const float* src, const bf16_t* delta, float* x1out, const float* w, const float* sc, const float* sh, bf16_t* dst, bool do_cs) {
;     ...
;     for (int row = X.gw; row < S; row += X.NGW) {
;         const f32x4* xr = (const f32x4*)(src + (size_t)row * D) + X.lane;
;         f32x4 v[8]; float ss = 0.f;
; #pragma unroll
;         for (int j = 0; j < 8; ++j) v[j] = __builtin_nontemporal_load(xr + 64 * j);
;         if (delta) {
;             const u32x2* dr = (const u32x2*)(delta + (size_t)row * D) + X.lane;
; #pragma unroll
;             for (int j = 0; j < 8; ++j) { const u32x2 d2 = dr[64 * j]; v[j][0] += bflo(d2.x); v[j][1] += bfhi(d2.x); v[j][2] += bflo(d2.y); v[j][3] += bfhi(d2.y); }
;             if (x1out) {
;                 f32x4* xo = (f32x4*)(x1out + (size_t)row * D) + X.lane;
; #pragma unroll
;                 for (int j = 0; j < 8; ++j) xo[64 * j] = v[j];
;             }
;         }
; #pragma unroll
;         for (int j = 0; j < 8; ++j) ss += (v[j][0] * v[j][0] + v[j][1] * v[j][1]) + (v[j][2] * v[j][2] + v[j][3] * v[j][3]);
;         const float r = rsqrtf(wave_sum(ss) * (1.f / D) + EPS);
;         u32x2* o8 = (u32x2*)(dst + (size_t)row * D) + X.lane;
; #pragma unroll
;         for (int j = 0; j < 8; ++j) {
;             const f32x4 y = (v[j] * r) * pa[j] + pb[j];
;             u32x2 p; p.x = pk2_rne(y[0], y[1]); p.y = pk2_rne(y[2], y[3]); o8[64 * j] = p;
;         }
	s_lshl_b64 s[12:13], s[48:49], 13
	s_add_u32 s12, s12, s52
	s_addc_u32 s13, s13, s53
	s_lshl_b64 s[14:15], s[48:49], 12
	s_add_u32 s14, s14, s90
	s_addc_u32 s15, s15, s91
	s_add_u32 s14, s14, 0x7700000
	s_addc_u32 s15, s15, 0
	v_lshlrev_b32_e32 v176, 4, v208
	v_add_u32_e32 v177, 0x1000, v176
	v_lshlrev_b32_e32 v178, 3, v208
	global_load_dwordx4 v[32:35], v176, s[12:13] offset:0 nt
	global_load_dwordx4 v[36:39], v176, s[12:13] offset:1024 nt
	global_load_dwordx4 v[40:43], v176, s[12:13] offset:2048 nt
	global_load_dwordx4 v[44:47], v176, s[12:13] offset:3072 nt
	global_load_dwordx4 v[48:51], v177, s[12:13] offset:0 nt
	global_load_dwordx4 v[52:55], v177, s[12:13] offset:1024 nt
	global_load_dwordx4 v[56:59], v177, s[12:13] offset:2048 nt
	global_load_dwordx4 v[60:63], v177, s[12:13] offset:3072 nt
	s_add_u32 s12, s12, s0
	s_addc_u32 s13, s13, s1
	global_load_dwordx4 v[130:133], v176, s[12:13] offset:0 nt
	global_load_dwordx4 v[134:137], v176, s[12:13] offset:1024 nt
	global_load_dwordx4 v[138:141], v176, s[12:13] offset:2048 nt
	global_load_dwordx4 v[142:145], v176, s[12:13] offset:3072 nt
	global_load_dwordx4 v[146:149], v177, s[12:13] offset:0 nt
	global_load_dwordx4 v[150:153], v177, s[12:13] offset:1024 nt
	global_load_dwordx4 v[154:157], v177, s[12:13] offset:2048 nt
	global_load_dwordx4 v[158:161], v177, s[12:13] offset:3072 nt
	s_add_u32 s12, s12, s0
	s_addc_u32 s13, s13, s1
	s_waitcnt vmcnt(8)
	v_pk_mul_f32 v[164:165], v[32:33], v[32:33]
	v_pk_mul_f32 v[166:167], v[34:35], v[34:35]
	v_pk_fma_f32 v[164:165], v[36:37], v[36:37], v[164:165]
	v_pk_fma_f32 v[166:167], v[38:39], v[38:39], v[166:167]
	v_pk_fma_f32 v[164:165], v[40:41], v[40:41], v[164:165]
	v_pk_fma_f32 v[166:167], v[42:43], v[42:43], v[166:167]
	v_pk_fma_f32 v[164:165], v[44:45], v[44:45], v[164:165]
	v_pk_fma_f32 v[166:167], v[46:47], v[46:47], v[166:167]
	v_pk_fma_f32 v[164:165], v[48:49], v[48:49], v[164:165]
	v_pk_fma_f32 v[166:167], v[50:51], v[50:51], v[166:167]
	v_pk_fma_f32 v[164:165], v[52:53], v[52:53], v[164:165]
	v_pk_fma_f32 v[166:167], v[54:55], v[54:55], v[166:167]
	v_pk_fma_f32 v[164:165], v[56:57], v[56:57], v[164:165]
	v_pk_fma_f32 v[166:167], v[58:59], v[58:59], v[166:167]
	v_pk_fma_f32 v[164:165], v[60:61], v[60:61], v[164:165]
	v_pk_fma_f32 v[166:167], v[62:63], v[62:63], v[166:167]
	v_pk_add_f32 v[164:165], v[164:165], v[166:167]
	s_nop 0
	v_add_f32_e32 v107, v164, v165
	ds_bpermute_b32 v162, v100, v107
	s_waitcnt lgkmcnt(0)
	v_add_f32_e32 v107, v107, v162
	ds_bpermute_b32 v162, v101, v107
	s_waitcnt lgkmcnt(0)
	v_add_f32_e32 v107, v107, v162
	ds_bpermute_b32 v162, v102, v107
	s_waitcnt lgkmcnt(0)
	v_add_f32_e32 v107, v107, v162
	ds_bpermute_b32 v162, v103, v107
	s_waitcnt lgkmcnt(0)
	v_add_f32_e32 v107, v107, v162
	ds_bpermute_b32 v162, v104, v107
	s_waitcnt lgkmcnt(0)
	v_add_f32_e32 v107, v107, v162
	ds_bpermute_b32 v162, v105, v107
	s_waitcnt lgkmcnt(0)
	v_add_f32_e32 v107, v107, v162
	v_fmamk_f32 v107, v107, 0x3a000000, v106
	v_mul_f32_e32 v162, 0x4b800000, v107
	v_cmp_gt_f32_e32 vcc, s2, v107
	s_nop 1
	v_cndmask_b32_e32 v107, v107, v162, vcc
	v_rsq_f32_e32 v107, v107
	s_nop 0
	v_mul_f32_e32 v162, 0x45800000, v107
	v_cndmask_b32_e32 v162, v107, v162, vcc
	v_pk_mul_f32 v[32:33], v[32:33], v[162:163] op_sel_hi:[1,0]
	v_pk_mul_f32 v[34:35], v[34:35], v[162:163] op_sel_hi:[1,0]
	v_pk_mul_f32 v[36:37], v[36:37], v[162:163] op_sel_hi:[1,0]
	v_pk_mul_f32 v[38:39], v[38:39], v[162:163] op_sel_hi:[1,0]
	v_pk_mul_f32 v[40:41], v[40:41], v[162:163] op_sel_hi:[1,0]
	v_pk_mul_f32 v[42:43], v[42:43], v[162:163] op_sel_hi:[1,0]
	v_pk_mul_f32 v[44:45], v[44:45], v[162:163] op_sel_hi:[1,0]
	v_pk_mul_f32 v[46:47], v[46:47], v[162:163] op_sel_hi:[1,0]
	v_pk_mul_f32 v[48:49], v[48:49], v[162:163] op_sel_hi:[1,0]
	v_pk_mul_f32 v[50:51], v[50:51], v[162:163] op_sel_hi:[1,0]
	v_pk_mul_f32 v[52:53], v[52:53], v[162:163] op_sel_hi:[1,0]
	v_pk_mul_f32 v[54:55], v[54:55], v[162:163] op_sel_hi:[1,0]
	v_pk_mul_f32 v[56:57], v[56:57], v[162:163] op_sel_hi:[1,0]
	v_pk_mul_f32 v[58:59], v[58:59], v[162:163] op_sel_hi:[1,0]
	v_pk_mul_f32 v[60:61], v[60:61], v[162:163] op_sel_hi:[1,0]
	v_pk_mul_f32 v[62:63], v[62:63], v[162:163] op_sel_hi:[1,0]
	v_pk_fma_f32 v[32:33], v[66:67], v[32:33], v[12:13]
	v_pk_fma_f32 v[34:35], v[64:65], v[34:35], v[14:15]
	v_pk_fma_f32 v[36:37], v[70:71], v[36:37], v[0:1]
	v_pk_fma_f32 v[38:39], v[68:69], v[38:39], v[2:3]
	v_pk_fma_f32 v[40:41], v[74:75], v[40:41], v[4:5]
	v_pk_fma_f32 v[42:43], v[72:73], v[42:43], v[6:7]
	v_pk_fma_f32 v[44:45], v[78:79], v[44:45], v[8:9]
	v_pk_fma_f32 v[46:47], v[76:77], v[46:47], v[10:11]
	v_pk_fma_f32 v[48:49], v[82:83], v[48:49], v[16:17]
	v_pk_fma_f32 v[50:51], v[80:81], v[50:51], v[18:19]
	v_pk_fma_f32 v[52:53], v[86:87], v[52:53], v[20:21]
	v_pk_fma_f32 v[54:55], v[84:85], v[54:55], v[22:23]
	v_pk_fma_f32 v[56:57], v[90:91], v[56:57], v[24:25]
	v_pk_fma_f32 v[58:59], v[88:89], v[58:59], v[26:27]
	v_pk_fma_f32 v[60:61], v[94:95], v[60:61], v[28:29]
	v_pk_fma_f32 v[62:63], v[92:93], v[62:63], v[30:31]
	v_cvt_pk_bf16_f32 v32, v32, v33
	v_cvt_pk_bf16_f32 v33, v34, v35
	v_cvt_pk_bf16_f32 v36, v36, v37
	v_cvt_pk_bf16_f32 v37, v38, v39
	v_cvt_pk_bf16_f32 v40, v40, v41
	v_cvt_pk_bf16_f32 v41, v42, v43
	v_cvt_pk_bf16_f32 v44, v44, v45
	v_cvt_pk_bf16_f32 v45, v46, v47
	v_cvt_pk_bf16_f32 v48, v48, v49
	v_cvt_pk_bf16_f32 v49, v50, v51
	v_cvt_pk_bf16_f32 v52, v52, v53
	v_cvt_pk_bf16_f32 v53, v54, v55
	v_cvt_pk_bf16_f32 v56, v56, v57
	v_cvt_pk_bf16_f32 v57, v58, v59
	v_cvt_pk_bf16_f32 v60, v60, v61
	v_cvt_pk_bf16_f32 v61, v62, v63
	global_store_dwordx2 v178, v[32:33], s[14:15] offset:0
	global_store_dwordx2 v178, v[36:37], s[14:15] offset:512
	global_store_dwordx2 v178, v[40:41], s[14:15] offset:1024
	global_store_dwordx2 v178, v[44:45], s[14:15] offset:1536
	global_store_dwordx2 v178, v[48:49], s[14:15] offset:2048
	global_store_dwordx2 v178, v[52:53], s[14:15] offset:2560
	global_store_dwordx2 v178, v[56:57], s[14:15] offset:3072
	global_store_dwordx2 v178, v[60:61], s[14:15] offset:3584
	s_add_u32 s14, s14, s4
	s_addc_u32 s15, s15, s5
	global_load_dwordx4 v[32:35], v176, s[12:13] offset:0 nt
	global_load_dwordx4 v[36:39], v176, s[12:13] offset:1024 nt
	global_load_dwordx4 v[40:43], v176, s[12:13] offset:2048 nt
	global_load_dwordx4 v[44:47], v176, s[12:13] offset:3072 nt
	global_load_dwordx4 v[48:51], v177, s[12:13] offset:0 nt
	global_load_dwordx4 v[52:55], v177, s[12:13] offset:1024 nt
	global_load_dwordx4 v[56:59], v177, s[12:13] offset:2048 nt
	global_load_dwordx4 v[60:63], v177, s[12:13] offset:3072 nt
	s_add_u32 s12, s12, s0
	s_addc_u32 s13, s13, s1
	s_waitcnt vmcnt(16)
; __device__ __forceinline__ unsigned pk2_rne(float lo, float hi) { const f32x2_t f = {lo, hi}; return __builtin_bit_cast(unsigned, __builtin_convertvector(f, bf16x2_t)); }
; __device__ __forceinline__ float bflo(unsigned w) { return __uint_as_float(w << 16); }
; __device__ __forceinline__ float bfhi(unsigned w) { return __uint_as_float(w & 0xffff0000u); }
; __device__ __forceinline__ void rows_norm_mod(Ctx& X, const float* src, const bf16_t* delta, float* x1out, const float* w, const float* sc, const float* sh, bf16_t* dst, bool do_cs) {
;     ...
;         const f32x4* xr = (const f32x4*)(src + (size_t)row * D) + X.lane;
;         f32x4 v[8]; float ss = 0.f;
; #pragma unroll
;         for (int j = 0; j < 8; ++j) v[j] = __builtin_nontemporal_load(xr + 64 * j);
;         if (delta) {
;             const u32x2* dr = (const u32x2*)(delta + (size_t)row * D) + X.lane;
; #pragma unroll
;             for (int j = 0; j < 8; ++j) { const u32x2 d2 = dr[64 * j]; v[j][0] += bflo(d2.x); v[j][1] += bfhi(d2.x); v[j][2] += bflo(d2.y); v[j][3] += bfhi(d2.y); }
;             if (x1out) {
;                 f32x4* xo = (f32x4*)(x1out + (size_t)row * D) + X.lane;
; #pragma unroll
;                 for (int j = 0; j < 8; ++j) xo[64 * j] = v[j];
;             }
;         }
; #pragma unroll
;         for (int j = 0; j < 8; ++j) ss += (v[j][0] * v[j][0] + v[j][1] * v[j][1]) + (v[j][2] * v[j][2] + v[j][3] * v[j][3]);
;         const float r = rsqrtf(wave_sum(ss) * (1.f / D) + EPS);
;         u32x2* o8 = (u32x2*)(dst + (size_t)row * D) + X.lane;
; #pragma unroll
;         for (int j = 0; j < 8; ++j) {
;             const f32x4 y = (v[j] * r) * pa[j] + pb[j];
;             u32x2 p; p.x = pk2_rne(y[0], y[1]); p.y = pk2_rne(y[2], y[3]); o8[64 * j] = p;
;         }
	v_pk_mul_f32 v[164:165], v[130:131], v[130:131]
	v_pk_mul_f32 v[166:167], v[132:133], v[132:133]
	v_pk_fma_f32 v[164:165], v[134:135], v[134:135], v[164:165]
	v_pk_fma_f32 v[166:167], v[136:137], v[136:137], v[166:167]
	v_pk_fma_f32 v[164:165], v[138:139], v[138:139], v[164:165]
	v_pk_fma_f32 v[166:167], v[140:141], v[140:141], v[166:167]
	v_pk_fma_f32 v[164:165], v[142:143], v[142:143], v[164:165]
	v_pk_fma_f32 v[166:167], v[144:145], v[144:145], v[166:167]
	v_pk_fma_f32 v[164:165], v[146:147], v[146:147], v[164:165]
	v_pk_fma_f32 v[166:167], v[148:149], v[148:149], v[166:167]
	v_pk_fma_f32 v[164:165], v[150:151], v[150:151], v[164:165]
	v_pk_fma_f32 v[166:167], v[152:153], v[152:153], v[166:167]
	v_pk_fma_f32 v[164:165], v[154:155], v[154:155], v[164:165]
	v_pk_fma_f32 v[166:167], v[156:157], v[156:157], v[166:167]
	v_pk_fma_f32 v[164:165], v[158:159], v[158:159], v[164:165]
	v_pk_fma_f32 v[166:167], v[160:161], v[160:161], v[166:167]
	v_pk_add_f32 v[164:165], v[164:165], v[166:167]
	s_nop 0
	v_add_f32_e32 v107, v164, v165
	ds_bpermute_b32 v162, v100, v107
	s_waitcnt lgkmcnt(0)
	v_add_f32_e32 v107, v107, v162
	ds_bpermute_b32 v162, v101, v107
	s_waitcnt lgkmcnt(0)
	v_add_f32_e32 v107, v107, v162
	ds_bpermute_b32 v162, v102, v107
	s_waitcnt lgkmcnt(0)
	v_add_f32_e32 v107, v107, v162
	ds_bpermute_b32 v162, v103, v107
	s_waitcnt lgkmcnt(0)
	v_add_f32_e32 v107, v107, v162
	ds_bpermute_b32 v162, v104, v107
	s_waitcnt lgkmcnt(0)
	v_add_f32_e32 v107, v107, v162
	ds_bpermute_b32 v162, v105, v107
	s_waitcnt lgkmcnt(0)
	v_add_f32_e32 v107, v107, v162
	v_fmamk_f32 v107, v107, 0x3a000000, v106
	v_mul_f32_e32 v162, 0x4b800000, v107
	v_cmp_gt_f32_e32 vcc, s2, v107
	s_nop 1
	v_cndmask_b32_e32 v107, v107, v162, vcc
	v_rsq_f32_e32 v107, v107
	s_nop 0
	v_mul_f32_e32 v162, 0x45800000, v107
	v_cndmask_b32_e32 v162, v107, v162, vcc
	v_pk_mul_f32 v[130:131], v[130:131], v[162:163] op_sel_hi:[1,0]
	v_pk_mul_f32 v[132:133], v[132:133], v[162:163] op_sel_hi:[1,0]
	v_pk_mul_f32 v[134:135], v[134:135], v[162:163] op_sel_hi:[1,0]
	v_pk_mul_f32 v[136:137], v[136:137], v[162:163] op_sel_hi:[1,0]
	v_pk_mul_f32 v[138:139], v[138:139], v[162:163] op_sel_hi:[1,0]
	v_pk_mul_f32 v[140:141], v[140:141], v[162:163] op_sel_hi:[1,0]
	v_pk_mul_f32 v[142:143], v[142:143], v[162:163] op_sel_hi:[1,0]
	v_pk_mul_f32 v[144:145], v[144:145], v[162:163] op_sel_hi:[1,0]
	v_pk_mul_f32 v[146:147], v[146:147], v[162:163] op_sel_hi:[1,0]
	v_pk_mul_f32 v[148:149], v[148:149], v[162:163] op_sel_hi:[1,0]
	v_pk_mul_f32 v[150:151], v[150:151], v[162:163] op_sel_hi:[1,0]
	v_pk_mul_f32 v[152:153], v[152:153], v[162:163] op_sel_hi:[1,0]
	v_pk_mul_f32 v[154:155], v[154:155], v[162:163] op_sel_hi:[1,0]
	v_pk_mul_f32 v[156:157], v[156:157], v[162:163] op_sel_hi:[1,0]
	v_pk_mul_f32 v[158:159], v[158:159], v[162:163] op_sel_hi:[1,0]
	v_pk_mul_f32 v[160:161], v[160:161], v[162:163] op_sel_hi:[1,0]
	v_pk_fma_f32 v[130:131], v[66:67], v[130:131], v[12:13]
	v_pk_fma_f32 v[132:133], v[64:65], v[132:133], v[14:15]
	v_pk_fma_f32 v[134:135], v[70:71], v[134:135], v[0:1]
	v_pk_fma_f32 v[136:137], v[68:69], v[136:137], v[2:3]
	v_pk_fma_f32 v[138:139], v[74:75], v[138:139], v[4:5]
	v_pk_fma_f32 v[140:141], v[72:73], v[140:141], v[6:7]
	v_pk_fma_f32 v[142:143], v[78:79], v[142:143], v[8:9]
	v_pk_fma_f32 v[144:145], v[76:77], v[144:145], v[10:11]
	v_pk_fma_f32 v[146:147], v[82:83], v[146:147], v[16:17]
	v_pk_fma_f32 v[148:149], v[80:81], v[148:149], v[18:19]
	v_pk_fma_f32 v[150:151], v[86:87], v[150:151], v[20:21]
	v_pk_fma_f32 v[152:153], v[84:85], v[152:153], v[22:23]
	v_pk_fma_f32 v[154:155], v[90:91], v[154:155], v[24:25]
	v_pk_fma_f32 v[156:157], v[88:89], v[156:157], v[26:27]
	v_pk_fma_f32 v[158:159], v[94:95], v[158:159], v[28:29]
	v_pk_fma_f32 v[160:161], v[92:93], v[160:161], v[30:31]
	v_cvt_pk_bf16_f32 v130, v130, v131
	v_cvt_pk_bf16_f32 v131, v132, v133
	v_cvt_pk_bf16_f32 v134, v134, v135
	v_cvt_pk_bf16_f32 v135, v136, v137
	v_cvt_pk_bf16_f32 v138, v138, v139
	v_cvt_pk_bf16_f32 v139, v140, v141
	v_cvt_pk_bf16_f32 v142, v142, v143
	v_cvt_pk_bf16_f32 v143, v144, v145
	v_cvt_pk_bf16_f32 v146, v146, v147
	v_cvt_pk_bf16_f32 v147, v148, v149
	v_cvt_pk_bf16_f32 v150, v150, v151
	v_cvt_pk_bf16_f32 v151, v152, v153
	v_cvt_pk_bf16_f32 v154, v154, v155
	v_cvt_pk_bf16_f32 v155, v156, v157
	v_cvt_pk_bf16_f32 v158, v158, v159
	v_cvt_pk_bf16_f32 v159, v160, v161
	global_store_dwordx2 v178, v[130:131], s[14:15] offset:0
	global_store_dwordx2 v178, v[134:135], s[14:15] offset:512
	global_store_dwordx2 v178, v[138:139], s[14:15] offset:1024
	global_store_dwordx2 v178, v[142:143], s[14:15] offset:1536
	global_store_dwordx2 v178, v[146:147], s[14:15] offset:2048
	global_store_dwordx2 v178, v[150:151], s[14:15] offset:2560
	global_store_dwordx2 v178, v[154:155], s[14:15] offset:3072
	global_store_dwordx2 v178, v[158:159], s[14:15] offset:3584
	s_add_u32 s14, s14, s4
	s_addc_u32 s15, s15, s5
	global_load_dwordx4 v[130:133], v176, s[12:13] offset:0 nt
	global_load_dwordx4 v[134:137], v176, s[12:13] offset:1024 nt
	global_load_dwordx4 v[138:141], v176, s[12:13] offset:2048 nt
	global_load_dwordx4 v[142:145], v176, s[12:13] offset:3072 nt
	global_load_dwordx4 v[146:149], v177, s[12:13] offset:0 nt
	global_load_dwordx4 v[150:153], v177, s[12:13] offset:1024 nt
	global_load_dwordx4 v[154:157], v177, s[12:13] offset:2048 nt
	global_load_dwordx4 v[158:161], v177, s[12:13] offset:3072 nt
	s_add_u32 s12, s12, s0
	s_addc_u32 s13, s13, s1
	s_waitcnt vmcnt(16)
; __device__ __forceinline__ unsigned pk2_rne(float lo, float hi) { const f32x2_t f = {lo, hi}; return __builtin_bit_cast(unsigned, __builtin_convertvector(f, bf16x2_t)); }
; __device__ __forceinline__ float bflo(unsigned w) { return __uint_as_float(w << 16); }
; __device__ __forceinline__ float bfhi(unsigned w) { return __uint_as_float(w & 0xffff0000u); }
; __device__ __forceinline__ void rows_norm_mod(Ctx& X, const float* src, const bf16_t* delta, float* x1out, const float* w, const float* sc, const float* sh, bf16_t* dst, bool do_cs) {
;     ...
;         const f32x4* xr = (const f32x4*)(src + (size_t)row * D) + X.lane;
;         f32x4 v[8]; float ss = 0.f;
; #pragma unroll
;         for (int j = 0; j < 8; ++j) v[j] = __builtin_nontemporal_load(xr + 64 * j);
;         if (delta) {
;             const u32x2* dr = (const u32x2*)(delta + (size_t)row * D) + X.lane;
; #pragma unroll
;             for (int j = 0; j < 8; ++j) { const u32x2 d2 = dr[64 * j]; v[j][0] += bflo(d2.x); v[j][1] += bfhi(d2.x); v[j][2] += bflo(d2.y); v[j][3] += bfhi(d2.y); }
;             if (x1out) {
;                 f32x4* xo = (f32x4*)(x1out + (size_t)row * D) + X.lane;
; #pragma unroll
;                 for (int j = 0; j < 8; ++j) xo[64 * j] = v[j];
;             }
;         }
; #pragma unroll
;         for (int j = 0; j < 8; ++j) ss += (v[j][0] * v[j][0] + v[j][1] * v[j][1]) + (v[j][2] * v[j][2] + v[j][3] * v[j][3]);
;         const float r = rsqrtf(wave_sum(ss) * (1.f / D) + EPS);
;         u32x2* o8 = (u32x2*)(dst + (size_t)row * D) + X.lane;
; #pragma unroll
;         for (int j = 0; j < 8; ++j) {
;             const f32x4 y = (v[j] * r) * pa[j] + pb[j];
;             u32x2 p; p.x = pk2_rne(y[0], y[1]); p.y = pk2_rne(y[2], y[3]); o8[64 * j] = p;
;         }
	v_pk_mul_f32 v[164:165], v[32:33], v[32:33]
	v_pk_mul_f32 v[166:167], v[34:35], v[34:35]
	v_pk_fma_f32 v[164:165], v[36:37], v[36:37], v[164:165]
	v_pk_fma_f32 v[166:167], v[38:39], v[38:39], v[166:167]
	v_pk_fma_f32 v[164:165], v[40:41], v[40:41], v[164:165]
	v_pk_fma_f32 v[166:167], v[42:43], v[42:43], v[166:167]
	v_pk_fma_f32 v[164:165], v[44:45], v[44:45], v[164:165]
	v_pk_fma_f32 v[166:167], v[46:47], v[46:47], v[166:167]
	v_pk_fma_f32 v[164:165], v[48:49], v[48:49], v[164:165]
	v_pk_fma_f32 v[166:167], v[50:51], v[50:51], v[166:167]
	v_pk_fma_f32 v[164:165], v[52:53], v[52:53], v[164:165]
	v_pk_fma_f32 v[166:167], v[54:55], v[54:55], v[166:167]
	v_pk_fma_f32 v[164:165], v[56:57], v[56:57], v[164:165]
	v_pk_fma_f32 v[166:167], v[58:59], v[58:59], v[166:167]
	v_pk_fma_f32 v[164:165], v[60:61], v[60:61], v[164:165]
	v_pk_fma_f32 v[166:167], v[62:63], v[62:63], v[166:167]
	v_pk_add_f32 v[164:165], v[164:165], v[166:167]
	s_nop 0
	v_add_f32_e32 v107, v164, v165
	ds_bpermute_b32 v162, v100, v107
	s_waitcnt lgkmcnt(0)
	v_add_f32_e32 v107, v107, v162
	ds_bpermute_b32 v162, v101, v107
	s_waitcnt lgkmcnt(0)
	v_add_f32_e32 v107, v107, v162
	ds_bpermute_b32 v162, v102, v107
	s_waitcnt lgkmcnt(0)
	v_add_f32_e32 v107, v107, v162
	ds_bpermute_b32 v162, v103, v107
	s_waitcnt lgkmcnt(0)
	v_add_f32_e32 v107, v107, v162
	ds_bpermute_b32 v162, v104, v107
	s_waitcnt lgkmcnt(0)
	v_add_f32_e32 v107, v107, v162
	ds_bpermute_b32 v162, v105, v107
	s_waitcnt lgkmcnt(0)
	v_add_f32_e32 v107, v107, v162
	v_fmamk_f32 v107, v107, 0x3a000000, v106
	v_mul_f32_e32 v162, 0x4b800000, v107
	v_cmp_gt_f32_e32 vcc, s2, v107
	s_nop 1
	v_cndmask_b32_e32 v107, v107, v162, vcc
	v_rsq_f32_e32 v107, v107
	s_nop 0
	v_mul_f32_e32 v162, 0x45800000, v107
	v_cndmask_b32_e32 v162, v107, v162, vcc
	v_pk_mul_f32 v[32:33], v[32:33], v[162:163] op_sel_hi:[1,0]
	v_pk_mul_f32 v[34:35], v[34:35], v[162:163] op_sel_hi:[1,0]
	v_pk_mul_f32 v[36:37], v[36:37], v[162:163] op_sel_hi:[1,0]
	v_pk_mul_f32 v[38:39], v[38:39], v[162:163] op_sel_hi:[1,0]
	v_pk_mul_f32 v[40:41], v[40:41], v[162:163] op_sel_hi:[1,0]
	v_pk_mul_f32 v[42:43], v[42:43], v[162:163] op_sel_hi:[1,0]
	v_pk_mul_f32 v[44:45], v[44:45], v[162:163] op_sel_hi:[1,0]
	v_pk_mul_f32 v[46:47], v[46:47], v[162:163] op_sel_hi:[1,0]
	v_pk_mul_f32 v[48:49], v[48:49], v[162:163] op_sel_hi:[1,0]
	v_pk_mul_f32 v[50:51], v[50:51], v[162:163] op_sel_hi:[1,0]
	v_pk_mul_f32 v[52:53], v[52:53], v[162:163] op_sel_hi:[1,0]
	v_pk_mul_f32 v[54:55], v[54:55], v[162:163] op_sel_hi:[1,0]
	v_pk_mul_f32 v[56:57], v[56:57], v[162:163] op_sel_hi:[1,0]
	v_pk_mul_f32 v[58:59], v[58:59], v[162:163] op_sel_hi:[1,0]
	v_pk_mul_f32 v[60:61], v[60:61], v[162:163] op_sel_hi:[1,0]
	v_pk_mul_f32 v[62:63], v[62:63], v[162:163] op_sel_hi:[1,0]
	v_pk_fma_f32 v[32:33], v[66:67], v[32:33], v[12:13]
	v_pk_fma_f32 v[34:35], v[64:65], v[34:35], v[14:15]
	v_pk_fma_f32 v[36:37], v[70:71], v[36:37], v[0:1]
	v_pk_fma_f32 v[38:39], v[68:69], v[38:39], v[2:3]
	v_pk_fma_f32 v[40:41], v[74:75], v[40:41], v[4:5]
	v_pk_fma_f32 v[42:43], v[72:73], v[42:43], v[6:7]
	v_pk_fma_f32 v[44:45], v[78:79], v[44:45], v[8:9]
	v_pk_fma_f32 v[46:47], v[76:77], v[46:47], v[10:11]
	v_pk_fma_f32 v[48:49], v[82:83], v[48:49], v[16:17]
	v_pk_fma_f32 v[50:51], v[80:81], v[50:51], v[18:19]
	v_pk_fma_f32 v[52:53], v[86:87], v[52:53], v[20:21]
	v_pk_fma_f32 v[54:55], v[84:85], v[54:55], v[22:23]
	v_pk_fma_f32 v[56:57], v[90:91], v[56:57], v[24:25]
	v_pk_fma_f32 v[58:59], v[88:89], v[58:59], v[26:27]
	v_pk_fma_f32 v[60:61], v[94:95], v[60:61], v[28:29]
	v_pk_fma_f32 v[62:63], v[92:93], v[62:63], v[30:31]
	v_cvt_pk_bf16_f32 v32, v32, v33
	v_cvt_pk_bf16_f32 v33, v34, v35
	v_cvt_pk_bf16_f32 v36, v36, v37
	v_cvt_pk_bf16_f32 v37, v38, v39
	v_cvt_pk_bf16_f32 v40, v40, v41
	v_cvt_pk_bf16_f32 v41, v42, v43
	v_cvt_pk_bf16_f32 v44, v44, v45
	v_cvt_pk_bf16_f32 v45, v46, v47
	v_cvt_pk_bf16_f32 v48, v48, v49
	v_cvt_pk_bf16_f32 v49, v50, v51
	v_cvt_pk_bf16_f32 v52, v52, v53
	v_cvt_pk_bf16_f32 v53, v54, v55
	v_cvt_pk_bf16_f32 v56, v56, v57
	v_cvt_pk_bf16_f32 v57, v58, v59
	v_cvt_pk_bf16_f32 v60, v60, v61
	v_cvt_pk_bf16_f32 v61, v62, v63
	global_store_dwordx2 v178, v[32:33], s[14:15] offset:0
	global_store_dwordx2 v178, v[36:37], s[14:15] offset:512
	global_store_dwordx2 v178, v[40:41], s[14:15] offset:1024
	global_store_dwordx2 v178, v[44:45], s[14:15] offset:1536
	global_store_dwordx2 v178, v[48:49], s[14:15] offset:2048
	global_store_dwordx2 v178, v[52:53], s[14:15] offset:2560
	global_store_dwordx2 v178, v[56:57], s[14:15] offset:3072
	global_store_dwordx2 v178, v[60:61], s[14:15] offset:3584
	s_add_u32 s14, s14, s4
	s_addc_u32 s15, s15, s5
	global_load_dwordx4 v[32:35], v176, s[12:13] offset:0 nt
	global_load_dwordx4 v[36:39], v176, s[12:13] offset:1024 nt
	global_load_dwordx4 v[40:43], v176, s[12:13] offset:2048 nt
	global_load_dwordx4 v[44:47], v176, s[12:13] offset:3072 nt
	global_load_dwordx4 v[48:51], v177, s[12:13] offset:0 nt
	global_load_dwordx4 v[52:55], v177, s[12:13] offset:1024 nt
	global_load_dwordx4 v[56:59], v177, s[12:13] offset:2048 nt
	global_load_dwordx4 v[60:63], v177, s[12:13] offset:3072 nt
	s_add_u32 s12, s12, s0
	s_addc_u32 s13, s13, s1
	s_waitcnt vmcnt(16)
; __device__ __forceinline__ unsigned pk2_rne(float lo, float hi) { const f32x2_t f = {lo, hi}; return __builtin_bit_cast(unsigned, __builtin_convertvector(f, bf16x2_t)); }
; __device__ __forceinline__ float bflo(unsigned w) { return __uint_as_float(w << 16); }
; __device__ __forceinline__ float bfhi(unsigned w) { return __uint_as_float(w & 0xffff0000u); }
; __device__ __forceinline__ void rows_norm_mod(Ctx& X, const float* src, const bf16_t* delta, float* x1out, const float* w, const float* sc, const float* sh, bf16_t* dst, bool do_cs) {
;     ...
;         const f32x4* xr = (const f32x4*)(src + (size_t)row * D) + X.lane;
;         f32x4 v[8]; float ss = 0.f;
; #pragma unroll
;         for (int j = 0; j < 8; ++j) v[j] = __builtin_nontemporal_load(xr + 64 * j);
;         if (delta) {
;             const u32x2* dr = (const u32x2*)(delta + (size_t)row * D) + X.lane;
; #pragma unroll
;             for (int j = 0; j < 8; ++j) { const u32x2 d2 = dr[64 * j]; v[j][0] += bflo(d2.x); v[j][1] += bfhi(d2.x); v[j][2] += bflo(d2.y); v[j][3] += bfhi(d2.y); }
;             if (x1out) {
;                 f32x4* xo = (f32x4*)(x1out + (size_t)row * D) + X.lane;
; #pragma unroll
;                 for (int j = 0; j < 8; ++j) xo[64 * j] = v[j];
;             }
;         }
; #pragma unroll
;         for (int j = 0; j < 8; ++j) ss += (v[j][0] * v[j][0] + v[j][1] * v[j][1]) + (v[j][2] * v[j][2] + v[j][3] * v[j][3]);
;         const float r = rsqrtf(wave_sum(ss) * (1.f / D) + EPS);
;         u32x2* o8 = (u32x2*)(dst + (size_t)row * D) + X.lane;
; #pragma unroll
;         for (int j = 0; j < 8; ++j) {
;             const f32x4 y = (v[j] * r) * pa[j] + pb[j];
;             u32x2 p; p.x = pk2_rne(y[0], y[1]); p.y = pk2_rne(y[2], y[3]); o8[64 * j] = p;
;         }
	v_pk_mul_f32 v[164:165], v[130:131], v[130:131]
	v_pk_mul_f32 v[166:167], v[132:133], v[132:133]
	v_pk_fma_f32 v[164:165], v[134:135], v[134:135], v[164:165]
	v_pk_fma_f32 v[166:167], v[136:137], v[136:137], v[166:167]
	v_pk_fma_f32 v[164:165], v[138:139], v[138:139], v[164:165]
	v_pk_fma_f32 v[166:167], v[140:141], v[140:141], v[166:167]
	v_pk_fma_f32 v[164:165], v[142:143], v[142:143], v[164:165]
	v_pk_fma_f32 v[166:167], v[144:145], v[144:145], v[166:167]
	v_pk_fma_f32 v[164:165], v[146:147], v[146:147], v[164:165]
	v_pk_fma_f32 v[166:167], v[148:149], v[148:149], v[166:167]
	v_pk_fma_f32 v[164:165], v[150:151], v[150:151], v[164:165]
	v_pk_fma_f32 v[166:167], v[152:153], v[152:153], v[166:167]
	v_pk_fma_f32 v[164:165], v[154:155], v[154:155], v[164:165]
	v_pk_fma_f32 v[166:167], v[156:157], v[156:157], v[166:167]
	v_pk_fma_f32 v[164:165], v[158:159], v[158:159], v[164:165]
	v_pk_fma_f32 v[166:167], v[160:161], v[160:161], v[166:167]
	v_pk_add_f32 v[164:165], v[164:165], v[166:167]
	s_nop 0
	v_add_f32_e32 v107, v164, v165
	ds_bpermute_b32 v162, v100, v107
	s_waitcnt lgkmcnt(0)
	v_add_f32_e32 v107, v107, v162
	ds_bpermute_b32 v162, v101, v107
	s_waitcnt lgkmcnt(0)
	v_add_f32_e32 v107, v107, v162
	ds_bpermute_b32 v162, v102, v107
	s_waitcnt lgkmcnt(0)
	v_add_f32_e32 v107, v107, v162
	ds_bpermute_b32 v162, v103, v107
	s_waitcnt lgkmcnt(0)
	v_add_f32_e32 v107, v107, v162
	ds_bpermute_b32 v162, v104, v107
	s_waitcnt lgkmcnt(0)
	v_add_f32_e32 v107, v107, v162
	ds_bpermute_b32 v162, v105, v107
	s_waitcnt lgkmcnt(0)
	v_add_f32_e32 v107, v107, v162
	v_fmamk_f32 v107, v107, 0x3a000000, v106
	v_mul_f32_e32 v162, 0x4b800000, v107
	v_cmp_gt_f32_e32 vcc, s2, v107
	s_nop 1
	v_cndmask_b32_e32 v107, v107, v162, vcc
	v_rsq_f32_e32 v107, v107
	s_nop 0
	v_mul_f32_e32 v162, 0x45800000, v107
	v_cndmask_b32_e32 v162, v107, v162, vcc
	v_pk_mul_f32 v[130:131], v[130:131], v[162:163] op_sel_hi:[1,0]
	v_pk_mul_f32 v[132:133], v[132:133], v[162:163] op_sel_hi:[1,0]
	v_pk_mul_f32 v[134:135], v[134:135], v[162:163] op_sel_hi:[1,0]
	v_pk_mul_f32 v[136:137], v[136:137], v[162:163] op_sel_hi:[1,0]
	v_pk_mul_f32 v[138:139], v[138:139], v[162:163] op_sel_hi:[1,0]
	v_pk_mul_f32 v[140:141], v[140:141], v[162:163] op_sel_hi:[1,0]
	v_pk_mul_f32 v[142:143], v[142:143], v[162:163] op_sel_hi:[1,0]
	v_pk_mul_f32 v[144:145], v[144:145], v[162:163] op_sel_hi:[1,0]
	v_pk_mul_f32 v[146:147], v[146:147], v[162:163] op_sel_hi:[1,0]
	v_pk_mul_f32 v[148:149], v[148:149], v[162:163] op_sel_hi:[1,0]
	v_pk_mul_f32 v[150:151], v[150:151], v[162:163] op_sel_hi:[1,0]
	v_pk_mul_f32 v[152:153], v[152:153], v[162:163] op_sel_hi:[1,0]
	v_pk_mul_f32 v[154:155], v[154:155], v[162:163] op_sel_hi:[1,0]
	v_pk_mul_f32 v[156:157], v[156:157], v[162:163] op_sel_hi:[1,0]
	v_pk_mul_f32 v[158:159], v[158:159], v[162:163] op_sel_hi:[1,0]
	v_pk_mul_f32 v[160:161], v[160:161], v[162:163] op_sel_hi:[1,0]
	v_pk_fma_f32 v[130:131], v[66:67], v[130:131], v[12:13]
	v_pk_fma_f32 v[132:133], v[64:65], v[132:133], v[14:15]
	v_pk_fma_f32 v[134:135], v[70:71], v[134:135], v[0:1]
	v_pk_fma_f32 v[136:137], v[68:69], v[136:137], v[2:3]
	v_pk_fma_f32 v[138:139], v[74:75], v[138:139], v[4:5]
	v_pk_fma_f32 v[140:141], v[72:73], v[140:141], v[6:7]
	v_pk_fma_f32 v[142:143], v[78:79], v[142:143], v[8:9]
	v_pk_fma_f32 v[144:145], v[76:77], v[144:145], v[10:11]
	v_pk_fma_f32 v[146:147], v[82:83], v[146:147], v[16:17]
	v_pk_fma_f32 v[148:149], v[80:81], v[148:149], v[18:19]
	v_pk_fma_f32 v[150:151], v[86:87], v[150:151], v[20:21]
	v_pk_fma_f32 v[152:153], v[84:85], v[152:153], v[22:23]
	v_pk_fma_f32 v[154:155], v[90:91], v[154:155], v[24:25]
	v_pk_fma_f32 v[156:157], v[88:89], v[156:157], v[26:27]
	v_pk_fma_f32 v[158:159], v[94:95], v[158:159], v[28:29]
	v_pk_fma_f32 v[160:161], v[92:93], v[160:161], v[30:31]
	v_cvt_pk_bf16_f32 v130, v130, v131
	v_cvt_pk_bf16_f32 v131, v132, v133
	v_cvt_pk_bf16_f32 v134, v134, v135
	v_cvt_pk_bf16_f32 v135, v136, v137
	v_cvt_pk_bf16_f32 v138, v138, v139
	v_cvt_pk_bf16_f32 v139, v140, v141
	v_cvt_pk_bf16_f32 v142, v142, v143
	v_cvt_pk_bf16_f32 v143, v144, v145
	v_cvt_pk_bf16_f32 v146, v146, v147
	v_cvt_pk_bf16_f32 v147, v148, v149
	v_cvt_pk_bf16_f32 v150, v150, v151
	v_cvt_pk_bf16_f32 v151, v152, v153
	v_cvt_pk_bf16_f32 v154, v154, v155
	v_cvt_pk_bf16_f32 v155, v156, v157
	v_cvt_pk_bf16_f32 v158, v158, v159
	v_cvt_pk_bf16_f32 v159, v160, v161
	global_store_dwordx2 v178, v[130:131], s[14:15] offset:0
	global_store_dwordx2 v178, v[134:135], s[14:15] offset:512
	global_store_dwordx2 v178, v[138:139], s[14:15] offset:1024
	global_store_dwordx2 v178, v[142:143], s[14:15] offset:1536
	global_store_dwordx2 v178, v[146:147], s[14:15] offset:2048
	global_store_dwordx2 v178, v[150:151], s[14:15] offset:2560
	global_store_dwordx2 v178, v[154:155], s[14:15] offset:3072
	global_store_dwordx2 v178, v[158:159], s[14:15] offset:3584
	s_add_u32 s14, s14, s4
	s_addc_u32 s15, s15, s5
	global_load_dwordx4 v[130:133], v176, s[12:13] offset:0 nt
	global_load_dwordx4 v[134:137], v176, s[12:13] offset:1024 nt
	global_load_dwordx4 v[138:141], v176, s[12:13] offset:2048 nt
	global_load_dwordx4 v[142:145], v176, s[12:13] offset:3072 nt
	global_load_dwordx4 v[146:149], v177, s[12:13] offset:0 nt
	global_load_dwordx4 v[150:153], v177, s[12:13] offset:1024 nt
	global_load_dwordx4 v[154:157], v177, s[12:13] offset:2048 nt
	global_load_dwordx4 v[158:161], v177, s[12:13] offset:3072 nt
	s_add_u32 s12, s12, s0
	s_addc_u32 s13, s13, s1
	s_waitcnt vmcnt(16)
; __device__ __forceinline__ unsigned pk2_rne(float lo, float hi) { const f32x2_t f = {lo, hi}; return __builtin_bit_cast(unsigned, __builtin_convertvector(f, bf16x2_t)); }
; __device__ __forceinline__ float bflo(unsigned w) { return __uint_as_float(w << 16); }
; __device__ __forceinline__ float bfhi(unsigned w) { return __uint_as_float(w & 0xffff0000u); }
; __device__ __forceinline__ void rows_norm_mod(Ctx& X, const float* src, const bf16_t* delta, float* x1out, const float* w, const float* sc, const float* sh, bf16_t* dst, bool do_cs) {
;     ...
;         const f32x4* xr = (const f32x4*)(src + (size_t)row * D) + X.lane;
;         f32x4 v[8]; float ss = 0.f;
; #pragma unroll
;         for (int j = 0; j < 8; ++j) v[j] = __builtin_nontemporal_load(xr + 64 * j);
;         if (delta) {
;             const u32x2* dr = (const u32x2*)(delta + (size_t)row * D) + X.lane;
; #pragma unroll
;             for (int j = 0; j < 8; ++j) { const u32x2 d2 = dr[64 * j]; v[j][0] += bflo(d2.x); v[j][1] += bfhi(d2.x); v[j][2] += bflo(d2.y); v[j][3] += bfhi(d2.y); }
;             if (x1out) {
;                 f32x4* xo = (f32x4*)(x1out + (size_t)row * D) + X.lane;
; #pragma unroll
;                 for (int j = 0; j < 8; ++j) xo[64 * j] = v[j];
;             }
;         }
; #pragma unroll
;         for (int j = 0; j < 8; ++j) ss += (v[j][0] * v[j][0] + v[j][1] * v[j][1]) + (v[j][2] * v[j][2] + v[j][3] * v[j][3]);
;         const float r = rsqrtf(wave_sum(ss) * (1.f / D) + EPS);
;         u32x2* o8 = (u32x2*)(dst + (size_t)row * D) + X.lane;
; #pragma unroll
;         for (int j = 0; j < 8; ++j) {
;             const f32x4 y = (v[j] * r) * pa[j] + pb[j];
;             u32x2 p; p.x = pk2_rne(y[0], y[1]); p.y = pk2_rne(y[2], y[3]); o8[64 * j] = p;
;         }
	v_pk_mul_f32 v[164:165], v[32:33], v[32:33]
	v_pk_mul_f32 v[166:167], v[34:35], v[34:35]
	v_pk_fma_f32 v[164:165], v[36:37], v[36:37], v[164:165]
	v_pk_fma_f32 v[166:167], v[38:39], v[38:39], v[166:167]
	v_pk_fma_f32 v[164:165], v[40:41], v[40:41], v[164:165]
	v_pk_fma_f32 v[166:167], v[42:43], v[42:43], v[166:167]
	v_pk_fma_f32 v[164:165], v[44:45], v[44:45], v[164:165]
	v_pk_fma_f32 v[166:167], v[46:47], v[46:47], v[166:167]
	v_pk_fma_f32 v[164:165], v[48:49], v[48:49], v[164:165]
	v_pk_fma_f32 v[166:167], v[50:51], v[50:51], v[166:167]
	v_pk_fma_f32 v[164:165], v[52:53], v[52:53], v[164:165]
	v_pk_fma_f32 v[166:167], v[54:55], v[54:55], v[166:167]
	v_pk_fma_f32 v[164:165], v[56:57], v[56:57], v[164:165]
	v_pk_fma_f32 v[166:167], v[58:59], v[58:59], v[166:167]
	v_pk_fma_f32 v[164:165], v[60:61], v[60:61], v[164:165]
	v_pk_fma_f32 v[166:167], v[62:63], v[62:63], v[166:167]
	v_pk_add_f32 v[164:165], v[164:165], v[166:167]
	s_nop 0
	v_add_f32_e32 v107, v164, v165
	ds_bpermute_b32 v162, v100, v107
	s_waitcnt lgkmcnt(0)
	v_add_f32_e32 v107, v107, v162
	ds_bpermute_b32 v162, v101, v107
	s_waitcnt lgkmcnt(0)
	v_add_f32_e32 v107, v107, v162
	ds_bpermute_b32 v162, v102, v107
	s_waitcnt lgkmcnt(0)
	v_add_f32_e32 v107, v107, v162
	ds_bpermute_b32 v162, v103, v107
	s_waitcnt lgkmcnt(0)
	v_add_f32_e32 v107, v107, v162
	ds_bpermute_b32 v162, v104, v107
	s_waitcnt lgkmcnt(0)
	v_add_f32_e32 v107, v107, v162
	ds_bpermute_b32 v162, v105, v107
	s_waitcnt lgkmcnt(0)
	v_add_f32_e32 v107, v107, v162
	v_fmamk_f32 v107, v107, 0x3a000000, v106
	v_mul_f32_e32 v162, 0x4b800000, v107
	v_cmp_gt_f32_e32 vcc, s2, v107
	s_nop 1
	v_cndmask_b32_e32 v107, v107, v162, vcc
	v_rsq_f32_e32 v107, v107
	s_nop 0
	v_mul_f32_e32 v162, 0x45800000, v107
	v_cndmask_b32_e32 v162, v107, v162, vcc
	v_pk_mul_f32 v[32:33], v[32:33], v[162:163] op_sel_hi:[1,0]
	v_pk_mul_f32 v[34:35], v[34:35], v[162:163] op_sel_hi:[1,0]
	v_pk_mul_f32 v[36:37], v[36:37], v[162:163] op_sel_hi:[1,0]
	v_pk_mul_f32 v[38:39], v[38:39], v[162:163] op_sel_hi:[1,0]
	v_pk_mul_f32 v[40:41], v[40:41], v[162:163] op_sel_hi:[1,0]
	v_pk_mul_f32 v[42:43], v[42:43], v[162:163] op_sel_hi:[1,0]
	v_pk_mul_f32 v[44:45], v[44:45], v[162:163] op_sel_hi:[1,0]
	v_pk_mul_f32 v[46:47], v[46:47], v[162:163] op_sel_hi:[1,0]
	v_pk_mul_f32 v[48:49], v[48:49], v[162:163] op_sel_hi:[1,0]
	v_pk_mul_f32 v[50:51], v[50:51], v[162:163] op_sel_hi:[1,0]
	v_pk_mul_f32 v[52:53], v[52:53], v[162:163] op_sel_hi:[1,0]
	v_pk_mul_f32 v[54:55], v[54:55], v[162:163] op_sel_hi:[1,0]
	v_pk_mul_f32 v[56:57], v[56:57], v[162:163] op_sel_hi:[1,0]
	v_pk_mul_f32 v[58:59], v[58:59], v[162:163] op_sel_hi:[1,0]
	v_pk_mul_f32 v[60:61], v[60:61], v[162:163] op_sel_hi:[1,0]
	v_pk_mul_f32 v[62:63], v[62:63], v[162:163] op_sel_hi:[1,0]
	v_pk_fma_f32 v[32:33], v[66:67], v[32:33], v[12:13]
	v_pk_fma_f32 v[34:35], v[64:65], v[34:35], v[14:15]
	v_pk_fma_f32 v[36:37], v[70:71], v[36:37], v[0:1]
	v_pk_fma_f32 v[38:39], v[68:69], v[38:39], v[2:3]
	v_pk_fma_f32 v[40:41], v[74:75], v[40:41], v[4:5]
	v_pk_fma_f32 v[42:43], v[72:73], v[42:43], v[6:7]
	v_pk_fma_f32 v[44:45], v[78:79], v[44:45], v[8:9]
	v_pk_fma_f32 v[46:47], v[76:77], v[46:47], v[10:11]
	v_pk_fma_f32 v[48:49], v[82:83], v[48:49], v[16:17]
	v_pk_fma_f32 v[50:51], v[80:81], v[50:51], v[18:19]
	v_pk_fma_f32 v[52:53], v[86:87], v[52:53], v[20:21]
	v_pk_fma_f32 v[54:55], v[84:85], v[54:55], v[22:23]
	v_pk_fma_f32 v[56:57], v[90:91], v[56:57], v[24:25]
	v_pk_fma_f32 v[58:59], v[88:89], v[58:59], v[26:27]
	v_pk_fma_f32 v[60:61], v[94:95], v[60:61], v[28:29]
	v_pk_fma_f32 v[62:63], v[92:93], v[62:63], v[30:31]
	v_cvt_pk_bf16_f32 v32, v32, v33
	v_cvt_pk_bf16_f32 v33, v34, v35
	v_cvt_pk_bf16_f32 v36, v36, v37
	v_cvt_pk_bf16_f32 v37, v38, v39
	v_cvt_pk_bf16_f32 v40, v40, v41
	v_cvt_pk_bf16_f32 v41, v42, v43
	v_cvt_pk_bf16_f32 v44, v44, v45
	v_cvt_pk_bf16_f32 v45, v46, v47
	v_cvt_pk_bf16_f32 v48, v48, v49
	v_cvt_pk_bf16_f32 v49, v50, v51
	v_cvt_pk_bf16_f32 v52, v52, v53
	v_cvt_pk_bf16_f32 v53, v54, v55
	v_cvt_pk_bf16_f32 v56, v56, v57
	v_cvt_pk_bf16_f32 v57, v58, v59
	v_cvt_pk_bf16_f32 v60, v60, v61
	v_cvt_pk_bf16_f32 v61, v62, v63
	global_store_dwordx2 v178, v[32:33], s[14:15] offset:0
	global_store_dwordx2 v178, v[36:37], s[14:15] offset:512
	global_store_dwordx2 v178, v[40:41], s[14:15] offset:1024
	global_store_dwordx2 v178, v[44:45], s[14:15] offset:1536
	global_store_dwordx2 v178, v[48:49], s[14:15] offset:2048
	global_store_dwordx2 v178, v[52:53], s[14:15] offset:2560
	global_store_dwordx2 v178, v[56:57], s[14:15] offset:3072
	global_store_dwordx2 v178, v[60:61], s[14:15] offset:3584
	s_add_u32 s14, s14, s4
	s_addc_u32 s15, s15, s5
	global_load_dwordx4 v[32:35], v176, s[12:13] offset:0 nt
	global_load_dwordx4 v[36:39], v176, s[12:13] offset:1024 nt
	global_load_dwordx4 v[40:43], v176, s[12:13] offset:2048 nt
	global_load_dwordx4 v[44:47], v176, s[12:13] offset:3072 nt
	global_load_dwordx4 v[48:51], v177, s[12:13] offset:0 nt
	global_load_dwordx4 v[52:55], v177, s[12:13] offset:1024 nt
	global_load_dwordx4 v[56:59], v177, s[12:13] offset:2048 nt
	global_load_dwordx4 v[60:63], v177, s[12:13] offset:3072 nt
	s_add_u32 s12, s12, s0
	s_addc_u32 s13, s13, s1
	s_waitcnt vmcnt(16)
; __device__ __forceinline__ unsigned pk2_rne(float lo, float hi) { const f32x2_t f = {lo, hi}; return __builtin_bit_cast(unsigned, __builtin_convertvector(f, bf16x2_t)); }
; __device__ __forceinline__ float bflo(unsigned w) { return __uint_as_float(w << 16); }
; __device__ __forceinline__ float bfhi(unsigned w) { return __uint_as_float(w & 0xffff0000u); }
; __device__ __forceinline__ void rows_norm_mod(Ctx& X, const float* src, const bf16_t* delta, float* x1out, const float* w, const float* sc, const float* sh, bf16_t* dst, bool do_cs) {
;     ...
;         const f32x4* xr = (const f32x4*)(src + (size_t)row * D) + X.lane;
;         f32x4 v[8]; float ss = 0.f;
; #pragma unroll
;         for (int j = 0; j < 8; ++j) v[j] = __builtin_nontemporal_load(xr + 64 * j);
;         if (delta) {
;             const u32x2* dr = (const u32x2*)(delta + (size_t)row * D) + X.lane;
; #pragma unroll
;             for (int j = 0; j < 8; ++j) { const u32x2 d2 = dr[64 * j]; v[j][0] += bflo(d2.x); v[j][1] += bfhi(d2.x); v[j][2] += bflo(d2.y); v[j][3] += bfhi(d2.y); }
;             if (x1out) {
;                 f32x4* xo = (f32x4*)(x1out + (size_t)row * D) + X.lane;
; #pragma unroll
;                 for (int j = 0; j < 8; ++j) xo[64 * j] = v[j];
;             }
;         }
; #pragma unroll
;         for (int j = 0; j < 8; ++j) ss += (v[j][0] * v[j][0] + v[j][1] * v[j][1]) + (v[j][2] * v[j][2] + v[j][3] * v[j][3]);
;         const float r = rsqrtf(wave_sum(ss) * (1.f / D) + EPS);
;         u32x2* o8 = (u32x2*)(dst + (size_t)row * D) + X.lane;
; #pragma unroll
;         for (int j = 0; j < 8; ++j) {
;             const f32x4 y = (v[j] * r) * pa[j] + pb[j];
;             u32x2 p; p.x = pk2_rne(y[0], y[1]); p.y = pk2_rne(y[2], y[3]); o8[64 * j] = p;
;         }
	v_pk_mul_f32 v[164:165], v[130:131], v[130:131]
	v_pk_mul_f32 v[166:167], v[132:133], v[132:133]
	v_pk_fma_f32 v[164:165], v[134:135], v[134:135], v[164:165]
	v_pk_fma_f32 v[166:167], v[136:137], v[136:137], v[166:167]
	v_pk_fma_f32 v[164:165], v[138:139], v[138:139], v[164:165]
	v_pk_fma_f32 v[166:167], v[140:141], v[140:141], v[166:167]
	v_pk_fma_f32 v[164:165], v[142:143], v[142:143], v[164:165]
	v_pk_fma_f32 v[166:167], v[144:145], v[144:145], v[166:167]
	v_pk_fma_f32 v[164:165], v[146:147], v[146:147], v[164:165]
	v_pk_fma_f32 v[166:167], v[148:149], v[148:149], v[166:167]
	v_pk_fma_f32 v[164:165], v[150:151], v[150:151], v[164:165]
	v_pk_fma_f32 v[166:167], v[152:153], v[152:153], v[166:167]
	v_pk_fma_f32 v[164:165], v[154:155], v[154:155], v[164:165]
	v_pk_fma_f32 v[166:167], v[156:157], v[156:157], v[166:167]
	v_pk_fma_f32 v[164:165], v[158:159], v[158:159], v[164:165]
	v_pk_fma_f32 v[166:167], v[160:161], v[160:161], v[166:167]
	v_pk_add_f32 v[164:165], v[164:165], v[166:167]
	s_nop 0
	v_add_f32_e32 v107, v164, v165
	ds_bpermute_b32 v162, v100, v107
	s_waitcnt lgkmcnt(0)
	v_add_f32_e32 v107, v107, v162
	ds_bpermute_b32 v162, v101, v107
	s_waitcnt lgkmcnt(0)
	v_add_f32_e32 v107, v107, v162
	ds_bpermute_b32 v162, v102, v107
	s_waitcnt lgkmcnt(0)
	v_add_f32_e32 v107, v107, v162
	ds_bpermute_b32 v162, v103, v107
	s_waitcnt lgkmcnt(0)
	v_add_f32_e32 v107, v107, v162
	ds_bpermute_b32 v162, v104, v107
	s_waitcnt lgkmcnt(0)
	v_add_f32_e32 v107, v107, v162
	ds_bpermute_b32 v162, v105, v107
	s_waitcnt lgkmcnt(0)
	v_add_f32_e32 v107, v107, v162
	v_fmamk_f32 v107, v107, 0x3a000000, v106
	v_mul_f32_e32 v162, 0x4b800000, v107
	v_cmp_gt_f32_e32 vcc, s2, v107
	s_nop 1
	v_cndmask_b32_e32 v107, v107, v162, vcc
	v_rsq_f32_e32 v107, v107
	s_nop 0
	v_mul_f32_e32 v162, 0x45800000, v107
	v_cndmask_b32_e32 v162, v107, v162, vcc
	v_pk_mul_f32 v[130:131], v[130:131], v[162:163] op_sel_hi:[1,0]
	v_pk_mul_f32 v[132:133], v[132:133], v[162:163] op_sel_hi:[1,0]
	v_pk_mul_f32 v[134:135], v[134:135], v[162:163] op_sel_hi:[1,0]
	v_pk_mul_f32 v[136:137], v[136:137], v[162:163] op_sel_hi:[1,0]
	v_pk_mul_f32 v[138:139], v[138:139], v[162:163] op_sel_hi:[1,0]
	v_pk_mul_f32 v[140:141], v[140:141], v[162:163] op_sel_hi:[1,0]
	v_pk_mul_f32 v[142:143], v[142:143], v[162:163] op_sel_hi:[1,0]
	v_pk_mul_f32 v[144:145], v[144:145], v[162:163] op_sel_hi:[1,0]
	v_pk_mul_f32 v[146:147], v[146:147], v[162:163] op_sel_hi:[1,0]
	v_pk_mul_f32 v[148:149], v[148:149], v[162:163] op_sel_hi:[1,0]
	v_pk_mul_f32 v[150:151], v[150:151], v[162:163] op_sel_hi:[1,0]
	v_pk_mul_f32 v[152:153], v[152:153], v[162:163] op_sel_hi:[1,0]
	v_pk_mul_f32 v[154:155], v[154:155], v[162:163] op_sel_hi:[1,0]
	v_pk_mul_f32 v[156:157], v[156:157], v[162:163] op_sel_hi:[1,0]
	v_pk_mul_f32 v[158:159], v[158:159], v[162:163] op_sel_hi:[1,0]
	v_pk_mul_f32 v[160:161], v[160:161], v[162:163] op_sel_hi:[1,0]
	v_pk_fma_f32 v[130:131], v[66:67], v[130:131], v[12:13]
	v_pk_fma_f32 v[132:133], v[64:65], v[132:133], v[14:15]
	v_pk_fma_f32 v[134:135], v[70:71], v[134:135], v[0:1]
	v_pk_fma_f32 v[136:137], v[68:69], v[136:137], v[2:3]
	v_pk_fma_f32 v[138:139], v[74:75], v[138:139], v[4:5]
	v_pk_fma_f32 v[140:141], v[72:73], v[140:141], v[6:7]
	v_pk_fma_f32 v[142:143], v[78:79], v[142:143], v[8:9]
	v_pk_fma_f32 v[144:145], v[76:77], v[144:145], v[10:11]
	v_pk_fma_f32 v[146:147], v[82:83], v[146:147], v[16:17]
	v_pk_fma_f32 v[148:149], v[80:81], v[148:149], v[18:19]
	v_pk_fma_f32 v[150:151], v[86:87], v[150:151], v[20:21]
	v_pk_fma_f32 v[152:153], v[84:85], v[152:153], v[22:23]
	v_pk_fma_f32 v[154:155], v[90:91], v[154:155], v[24:25]
	v_pk_fma_f32 v[156:157], v[88:89], v[156:157], v[26:27]
	v_pk_fma_f32 v[158:159], v[94:95], v[158:159], v[28:29]
	v_pk_fma_f32 v[160:161], v[92:93], v[160:161], v[30:31]
	v_cvt_pk_bf16_f32 v130, v130, v131
	v_cvt_pk_bf16_f32 v131, v132, v133
	v_cvt_pk_bf16_f32 v134, v134, v135
	v_cvt_pk_bf16_f32 v135, v136, v137
	v_cvt_pk_bf16_f32 v138, v138, v139
	v_cvt_pk_bf16_f32 v139, v140, v141
	v_cvt_pk_bf16_f32 v142, v142, v143
	v_cvt_pk_bf16_f32 v143, v144, v145
	v_cvt_pk_bf16_f32 v146, v146, v147
	v_cvt_pk_bf16_f32 v147, v148, v149
	v_cvt_pk_bf16_f32 v150, v150, v151
	v_cvt_pk_bf16_f32 v151, v152, v153
	v_cvt_pk_bf16_f32 v154, v154, v155
	v_cvt_pk_bf16_f32 v155, v156, v157
	v_cvt_pk_bf16_f32 v158, v158, v159
	v_cvt_pk_bf16_f32 v159, v160, v161
	global_store_dwordx2 v178, v[130:131], s[14:15] offset:0
	global_store_dwordx2 v178, v[134:135], s[14:15] offset:512
	global_store_dwordx2 v178, v[138:139], s[14:15] offset:1024
	global_store_dwordx2 v178, v[142:143], s[14:15] offset:1536
	global_store_dwordx2 v178, v[146:147], s[14:15] offset:2048
	global_store_dwordx2 v178, v[150:151], s[14:15] offset:2560
	global_store_dwordx2 v178, v[154:155], s[14:15] offset:3072
	global_store_dwordx2 v178, v[158:159], s[14:15] offset:3584
	s_add_u32 s14, s14, s4
	s_addc_u32 s15, s15, s5
	global_load_dwordx4 v[130:133], v176, s[12:13] offset:0 nt
	global_load_dwordx4 v[134:137], v176, s[12:13] offset:1024 nt
	global_load_dwordx4 v[138:141], v176, s[12:13] offset:2048 nt
	global_load_dwordx4 v[142:145], v176, s[12:13] offset:3072 nt
	global_load_dwordx4 v[146:149], v177, s[12:13] offset:0 nt
	global_load_dwordx4 v[150:153], v177, s[12:13] offset:1024 nt
	global_load_dwordx4 v[154:157], v177, s[12:13] offset:2048 nt
	global_load_dwordx4 v[158:161], v177, s[12:13] offset:3072 nt
	s_add_u32 s12, s12, s0
	s_addc_u32 s13, s13, s1
	s_waitcnt vmcnt(16)
; __device__ __forceinline__ unsigned pk2_rne(float lo, float hi) { const f32x2_t f = {lo, hi}; return __builtin_bit_cast(unsigned, __builtin_convertvector(f, bf16x2_t)); }
; __device__ __forceinline__ void rows_norm_mod(Ctx& X, const float* src, const bf16_t* delta, float* x1out, const float* w, const float* sc, const float* sh, bf16_t* dst, bool do_cs) {
;     ...
;         for (int j = 0; j < 8; ++j) ss += (v[j][0] * v[j][0] + v[j][1] * v[j][1]) + (v[j][2] * v[j][2] + v[j][3] * v[j][3]);
;         const float r = rsqrtf(wave_sum(ss) * (1.f / D) + EPS);
;         u32x2* o8 = (u32x2*)(dst + (size_t)row * D) + X.lane;
; #pragma unroll
;         for (int j = 0; j < 8; ++j) {
;             const f32x4 y = (v[j] * r) * pa[j] + pb[j];
;             u32x2 p; p.x = pk2_rne(y[0], y[1]); p.y = pk2_rne(y[2], y[3]); o8[64 * j] = p;
;         }
	v_pk_mul_f32 v[164:165], v[32:33], v[32:33]
	v_pk_mul_f32 v[166:167], v[34:35], v[34:35]
	v_pk_fma_f32 v[164:165], v[36:37], v[36:37], v[164:165]
	v_pk_fma_f32 v[166:167], v[38:39], v[38:39], v[166:167]
	v_pk_fma_f32 v[164:165], v[40:41], v[40:41], v[164:165]
	v_pk_fma_f32 v[166:167], v[42:43], v[42:43], v[166:167]
	v_pk_fma_f32 v[164:165], v[44:45], v[44:45], v[164:165]
	v_pk_fma_f32 v[166:167], v[46:47], v[46:47], v[166:167]
	v_pk_fma_f32 v[164:165], v[48:49], v[48:49], v[164:165]
	v_pk_fma_f32 v[166:167], v[50:51], v[50:51], v[166:167]
	v_pk_fma_f32 v[164:165], v[52:53], v[52:53], v[164:165]
	v_pk_fma_f32 v[166:167], v[54:55], v[54:55], v[166:167]
	v_pk_fma_f32 v[164:165], v[56:57], v[56:57], v[164:165]
	v_pk_fma_f32 v[166:167], v[58:59], v[58:59], v[166:167]
	v_pk_fma_f32 v[164:165], v[60:61], v[60:61], v[164:165]
	v_pk_fma_f32 v[166:167], v[62:63], v[62:63], v[166:167]
	v_pk_add_f32 v[164:165], v[164:165], v[166:167]
	s_nop 0
	v_add_f32_e32 v107, v164, v165
	ds_bpermute_b32 v162, v100, v107
	s_waitcnt lgkmcnt(0)
	v_add_f32_e32 v107, v107, v162
	ds_bpermute_b32 v162, v101, v107
	s_waitcnt lgkmcnt(0)
	v_add_f32_e32 v107, v107, v162
	ds_bpermute_b32 v162, v102, v107
	s_waitcnt lgkmcnt(0)
	v_add_f32_e32 v107, v107, v162
	ds_bpermute_b32 v162, v103, v107
	s_waitcnt lgkmcnt(0)
	v_add_f32_e32 v107, v107, v162
	ds_bpermute_b32 v162, v104, v107
	s_waitcnt lgkmcnt(0)
	v_add_f32_e32 v107, v107, v162
	ds_bpermute_b32 v162, v105, v107
	s_waitcnt lgkmcnt(0)
	v_add_f32_e32 v107, v107, v162
	v_fmamk_f32 v107, v107, 0x3a000000, v106
	v_mul_f32_e32 v162, 0x4b800000, v107
	v_cmp_gt_f32_e32 vcc, s2, v107
	s_nop 1
	v_cndmask_b32_e32 v107, v107, v162, vcc
	v_rsq_f32_e32 v107, v107
	s_nop 0
	v_mul_f32_e32 v162, 0x45800000, v107
	v_cndmask_b32_e32 v162, v107, v162, vcc
	v_pk_mul_f32 v[32:33], v[32:33], v[162:163] op_sel_hi:[1,0]
	v_pk_mul_f32 v[34:35], v[34:35], v[162:163] op_sel_hi:[1,0]
	v_pk_mul_f32 v[36:37], v[36:37], v[162:163] op_sel_hi:[1,0]
	v_pk_mul_f32 v[38:39], v[38:39], v[162:163] op_sel_hi:[1,0]
	v_pk_mul_f32 v[40:41], v[40:41], v[162:163] op_sel_hi:[1,0]
	v_pk_mul_f32 v[42:43], v[42:43], v[162:163] op_sel_hi:[1,0]
	v_pk_mul_f32 v[44:45], v[44:45], v[162:163] op_sel_hi:[1,0]
	v_pk_mul_f32 v[46:47], v[46:47], v[162:163] op_sel_hi:[1,0]
	v_pk_mul_f32 v[48:49], v[48:49], v[162:163] op_sel_hi:[1,0]
	v_pk_mul_f32 v[50:51], v[50:51], v[162:163] op_sel_hi:[1,0]
	v_pk_mul_f32 v[52:53], v[52:53], v[162:163] op_sel_hi:[1,0]
	v_pk_mul_f32 v[54:55], v[54:55], v[162:163] op_sel_hi:[1,0]
	v_pk_mul_f32 v[56:57], v[56:57], v[162:163] op_sel_hi:[1,0]
	v_pk_mul_f32 v[58:59], v[58:59], v[162:163] op_sel_hi:[1,0]
	v_pk_mul_f32 v[60:61], v[60:61], v[162:163] op_sel_hi:[1,0]
	v_pk_mul_f32 v[62:63], v[62:63], v[162:163] op_sel_hi:[1,0]
	v_pk_fma_f32 v[32:33], v[66:67], v[32:33], v[12:13]
	v_pk_fma_f32 v[34:35], v[64:65], v[34:35], v[14:15]
	v_pk_fma_f32 v[36:37], v[70:71], v[36:37], v[0:1]
	v_pk_fma_f32 v[38:39], v[68:69], v[38:39], v[2:3]
	v_pk_fma_f32 v[40:41], v[74:75], v[40:41], v[4:5]
	v_pk_fma_f32 v[42:43], v[72:73], v[42:43], v[6:7]
	v_pk_fma_f32 v[44:45], v[78:79], v[44:45], v[8:9]
	v_pk_fma_f32 v[46:47], v[76:77], v[46:47], v[10:11]
	v_pk_fma_f32 v[48:49], v[82:83], v[48:49], v[16:17]
	v_pk_fma_f32 v[50:51], v[80:81], v[50:51], v[18:19]
	v_pk_fma_f32 v[52:53], v[86:87], v[52:53], v[20:21]
	v_pk_fma_f32 v[54:55], v[84:85], v[54:55], v[22:23]
	v_pk_fma_f32 v[56:57], v[90:91], v[56:57], v[24:25]
	v_pk_fma_f32 v[58:59], v[88:89], v[58:59], v[26:27]
	v_pk_fma_f32 v[60:61], v[94:95], v[60:61], v[28:29]
	v_pk_fma_f32 v[62:63], v[92:93], v[62:63], v[30:31]
	v_cvt_pk_bf16_f32 v32, v32, v33
	v_cvt_pk_bf16_f32 v33, v34, v35
	v_cvt_pk_bf16_f32 v36, v36, v37
	v_cvt_pk_bf16_f32 v37, v38, v39
	v_cvt_pk_bf16_f32 v40, v40, v41
	v_cvt_pk_bf16_f32 v41, v42, v43
	v_cvt_pk_bf16_f32 v44, v44, v45
	v_cvt_pk_bf16_f32 v45, v46, v47
	v_cvt_pk_bf16_f32 v48, v48, v49
	v_cvt_pk_bf16_f32 v49, v50, v51
	v_cvt_pk_bf16_f32 v52, v52, v53
	v_cvt_pk_bf16_f32 v53, v54, v55
	v_cvt_pk_bf16_f32 v56, v56, v57
	v_cvt_pk_bf16_f32 v57, v58, v59
	v_cvt_pk_bf16_f32 v60, v60, v61
	v_cvt_pk_bf16_f32 v61, v62, v63
	global_store_dwordx2 v178, v[32:33], s[14:15] offset:0
	global_store_dwordx2 v178, v[36:37], s[14:15] offset:512
	global_store_dwordx2 v178, v[40:41], s[14:15] offset:1024
	global_store_dwordx2 v178, v[44:45], s[14:15] offset:1536
	global_store_dwordx2 v178, v[48:49], s[14:15] offset:2048
	global_store_dwordx2 v178, v[52:53], s[14:15] offset:2560
	global_store_dwordx2 v178, v[56:57], s[14:15] offset:3072
	global_store_dwordx2 v178, v[60:61], s[14:15] offset:3584
	s_add_u32 s14, s14, s4
	s_addc_u32 s15, s15, s5
	s_waitcnt vmcnt(8)
; __device__ __forceinline__ unsigned pk2_rne(float lo, float hi) { const f32x2_t f = {lo, hi}; return __builtin_bit_cast(unsigned, __builtin_convertvector(f, bf16x2_t)); }
; __device__ __forceinline__ void rows_norm_mod(Ctx& X, const float* src, const bf16_t* delta, float* x1out, const float* w, const float* sc, const float* sh, bf16_t* dst, bool do_cs) {
;     ...
;         for (int j = 0; j < 8; ++j) ss += (v[j][0] * v[j][0] + v[j][1] * v[j][1]) + (v[j][2] * v[j][2] + v[j][3] * v[j][3]);
;         const float r = rsqrtf(wave_sum(ss) * (1.f / D) + EPS);
;         u32x2* o8 = (u32x2*)(dst + (size_t)row * D) + X.lane;
; #pragma unroll
;         for (int j = 0; j < 8; ++j) {
;             const f32x4 y = (v[j] * r) * pa[j] + pb[j];
;             u32x2 p; p.x = pk2_rne(y[0], y[1]); p.y = pk2_rne(y[2], y[3]); o8[64 * j] = p;
;         }
	v_pk_mul_f32 v[164:165], v[130:131], v[130:131]
	v_pk_mul_f32 v[166:167], v[132:133], v[132:133]
	v_pk_fma_f32 v[164:165], v[134:135], v[134:135], v[164:165]
	v_pk_fma_f32 v[166:167], v[136:137], v[136:137], v[166:167]
	v_pk_fma_f32 v[164:165], v[138:139], v[138:139], v[164:165]
	v_pk_fma_f32 v[166:167], v[140:141], v[140:141], v[166:167]
	v_pk_fma_f32 v[164:165], v[142:143], v[142:143], v[164:165]
	v_pk_fma_f32 v[166:167], v[144:145], v[144:145], v[166:167]
	v_pk_fma_f32 v[164:165], v[146:147], v[146:147], v[164:165]
	v_pk_fma_f32 v[166:167], v[148:149], v[148:149], v[166:167]
	v_pk_fma_f32 v[164:165], v[150:151], v[150:151], v[164:165]
	v_pk_fma_f32 v[166:167], v[152:153], v[152:153], v[166:167]
	v_pk_fma_f32 v[164:165], v[154:155], v[154:155], v[164:165]
	v_pk_fma_f32 v[166:167], v[156:157], v[156:157], v[166:167]
	v_pk_fma_f32 v[164:165], v[158:159], v[158:159], v[164:165]
	v_pk_fma_f32 v[166:167], v[160:161], v[160:161], v[166:167]
	v_pk_add_f32 v[164:165], v[164:165], v[166:167]
	s_nop 0
	v_add_f32_e32 v107, v164, v165
	ds_bpermute_b32 v162, v100, v107
	s_waitcnt lgkmcnt(0)
	v_add_f32_e32 v107, v107, v162
	ds_bpermute_b32 v162, v101, v107
	s_waitcnt lgkmcnt(0)
	v_add_f32_e32 v107, v107, v162
	ds_bpermute_b32 v162, v102, v107
	s_waitcnt lgkmcnt(0)
	v_add_f32_e32 v107, v107, v162
	ds_bpermute_b32 v162, v103, v107
	s_waitcnt lgkmcnt(0)
	v_add_f32_e32 v107, v107, v162
	ds_bpermute_b32 v162, v104, v107
	s_waitcnt lgkmcnt(0)
	v_add_f32_e32 v107, v107, v162
	ds_bpermute_b32 v162, v105, v107
	s_waitcnt lgkmcnt(0)
	v_add_f32_e32 v107, v107, v162
	v_fmamk_f32 v107, v107, 0x3a000000, v106
	v_mul_f32_e32 v162, 0x4b800000, v107
	v_cmp_gt_f32_e32 vcc, s2, v107
	s_nop 1
	v_cndmask_b32_e32 v107, v107, v162, vcc
	v_rsq_f32_e32 v107, v107
	s_nop 0
	v_mul_f32_e32 v162, 0x45800000, v107
	v_cndmask_b32_e32 v162, v107, v162, vcc
	v_pk_mul_f32 v[130:131], v[130:131], v[162:163] op_sel_hi:[1,0]
	v_pk_mul_f32 v[132:133], v[132:133], v[162:163] op_sel_hi:[1,0]
	v_pk_mul_f32 v[134:135], v[134:135], v[162:163] op_sel_hi:[1,0]
	v_pk_mul_f32 v[136:137], v[136:137], v[162:163] op_sel_hi:[1,0]
	v_pk_mul_f32 v[138:139], v[138:139], v[162:163] op_sel_hi:[1,0]
	v_pk_mul_f32 v[140:141], v[140:141], v[162:163] op_sel_hi:[1,0]
	v_pk_mul_f32 v[142:143], v[142:143], v[162:163] op_sel_hi:[1,0]
	v_pk_mul_f32 v[144:145], v[144:145], v[162:163] op_sel_hi:[1,0]
	v_pk_mul_f32 v[146:147], v[146:147], v[162:163] op_sel_hi:[1,0]
	v_pk_mul_f32 v[148:149], v[148:149], v[162:163] op_sel_hi:[1,0]
	v_pk_mul_f32 v[150:151], v[150:151], v[162:163] op_sel_hi:[1,0]
	v_pk_mul_f32 v[152:153], v[152:153], v[162:163] op_sel_hi:[1,0]
	v_pk_mul_f32 v[154:155], v[154:155], v[162:163] op_sel_hi:[1,0]
	v_pk_mul_f32 v[156:157], v[156:157], v[162:163] op_sel_hi:[1,0]
	v_pk_mul_f32 v[158:159], v[158:159], v[162:163] op_sel_hi:[1,0]
	v_pk_mul_f32 v[160:161], v[160:161], v[162:163] op_sel_hi:[1,0]
	v_pk_fma_f32 v[130:131], v[66:67], v[130:131], v[12:13]
	v_pk_fma_f32 v[132:133], v[64:65], v[132:133], v[14:15]
	v_pk_fma_f32 v[134:135], v[70:71], v[134:135], v[0:1]
	v_pk_fma_f32 v[136:137], v[68:69], v[136:137], v[2:3]
	v_pk_fma_f32 v[138:139], v[74:75], v[138:139], v[4:5]
	v_pk_fma_f32 v[140:141], v[72:73], v[140:141], v[6:7]
	v_pk_fma_f32 v[142:143], v[78:79], v[142:143], v[8:9]
	v_pk_fma_f32 v[144:145], v[76:77], v[144:145], v[10:11]
	v_pk_fma_f32 v[146:147], v[82:83], v[146:147], v[16:17]
	v_pk_fma_f32 v[148:149], v[80:81], v[148:149], v[18:19]
	v_pk_fma_f32 v[150:151], v[86:87], v[150:151], v[20:21]
	v_pk_fma_f32 v[152:153], v[84:85], v[152:153], v[22:23]
	v_pk_fma_f32 v[154:155], v[90:91], v[154:155], v[24:25]
	v_pk_fma_f32 v[156:157], v[88:89], v[156:157], v[26:27]
	v_pk_fma_f32 v[158:159], v[94:95], v[158:159], v[28:29]
	v_pk_fma_f32 v[160:161], v[92:93], v[160:161], v[30:31]
	v_cvt_pk_bf16_f32 v130, v130, v131
	v_cvt_pk_bf16_f32 v131, v132, v133
	v_cvt_pk_bf16_f32 v134, v134, v135
	v_cvt_pk_bf16_f32 v135, v136, v137
	v_cvt_pk_bf16_f32 v138, v138, v139
	v_cvt_pk_bf16_f32 v139, v140, v141
	v_cvt_pk_bf16_f32 v142, v142, v143
	v_cvt_pk_bf16_f32 v143, v144, v145
	v_cvt_pk_bf16_f32 v146, v146, v147
	v_cvt_pk_bf16_f32 v147, v148, v149
	v_cvt_pk_bf16_f32 v150, v150, v151
	v_cvt_pk_bf16_f32 v151, v152, v153
	v_cvt_pk_bf16_f32 v154, v154, v155
	v_cvt_pk_bf16_f32 v155, v156, v157
	v_cvt_pk_bf16_f32 v158, v158, v159
	v_cvt_pk_bf16_f32 v159, v160, v161
	global_store_dwordx2 v178, v[130:131], s[14:15] offset:0
	global_store_dwordx2 v178, v[134:135], s[14:15] offset:512
	global_store_dwordx2 v178, v[138:139], s[14:15] offset:1024
	global_store_dwordx2 v178, v[142:143], s[14:15] offset:1536
	global_store_dwordx2 v178, v[146:147], s[14:15] offset:2048
	global_store_dwordx2 v178, v[150:151], s[14:15] offset:2560
	global_store_dwordx2 v178, v[154:155], s[14:15] offset:3072
	global_store_dwordx2 v178, v[158:159], s[14:15] offset:3584
	s_add_u32 s14, s14, s4
	s_addc_u32 s15, s15, s5
	s_branch .LBB0_104

; __device__ __forceinline__ void rows_norm_mod(Ctx& X, const float* src, const bf16_t* delta, float* x1out, const float* w, const float* sc, const float* sh, bf16_t* dst, bool do_cs) {
;     ...
;     if (do_cs) {
;         const int gt = blockIdx.x * 512 + X.tid, NT = X.G * 512;
;         float* cs = (float*)(X.ws + WS_CS);
;         for (int idx = gt; idx < S * 16; idx += NT) {
;             const int rw = idx >> 4, i = idx & 15;
;             const float invf = 1.0f / powf(500000.0f, (float)(2 * i) * (1.0f / 32.0f));
;             const float ang = (float)X.pos[rw] * invf;
;             cs[(size_t)rw * 32 + i] = cosf(ang); cs[(size_t)rw * 32 + 16 + i] = sinf(ang);
;         }
.LBB0_104:
	s_cmp_eq_u32 s31, 2
	s_cbranch_scc1 .LBB0_116
	v_readlane_b32 s0, v245, 0
	v_readlane_b32 s1, v245, 1
	s_nop 0
	v_lshl_add_u32 v6, s0, 9, v209
	s_mov_b32 s0, 0x40000
	v_cmp_gt_i32_e32 vcc, s0, v6
	s_and_saveexec_b64 s[12:13], vcc
	s_cbranch_execz .LBB0_115
	v_and_b32_e32 v16, 15, v209
	v_lshlrev_b32_e32 v0, 1, v16
	v_cvt_f32_ubyte0_e32 v0, v0
	v_mul_f32_e32 v7, 0x3d000000, v0
	v_mov_b32_e32 v0, 0x48f42400
	v_cmp_eq_f32_e32 vcc, 0, v7
	s_mov_b32 s0, 0x3f2aaaab
	s_mov_b32 s1, 0x42b17218
	v_cndmask_b32_e64 v12, v0, 1.0, vcc
	v_frexp_mant_f32_e32 v0, v12
	v_cmp_gt_f32_e32 vcc, s0, v0
	s_mov_b32 s0, 0x3f317218
	s_mov_b32 s2, 0x3fb8aa3b
	v_cndmask_b32_e64 v1, 1.0, 2.0, vcc
	v_mul_f32_e32 v0, v0, v1
	v_add_f32_e32 v3, 1.0, v0
	v_rcp_f32_e32 v10, v3
	v_add_f32_e32 v1, -1.0, v3
	v_sub_f32_e32 v5, v0, v1
	v_add_f32_e32 v1, -1.0, v0
	v_mul_f32_e32 v11, v1, v10
	v_mul_f32_e32 v2, v3, v11
	v_fma_f32 v4, v11, v3, -v2
	v_fmac_f32_e32 v4, v11, v5
	v_add_f32_e32 v0, v2, v4
	v_sub_f32_e32 v3, v1, v0
	v_pk_add_f32 v[8:9], v[0:1], v[2:3] neg_lo:[0,1] neg_hi:[0,1]
	v_mov_b32_e32 v5, v0
	v_pk_add_f32 v[0:1], v[8:9], v[4:5] neg_lo:[0,1] neg_hi:[0,1]
	v_mov_b32_e32 v4, 0x3e91f4c4
	v_add_f32_e32 v0, v0, v1
	v_add_f32_e32 v0, v3, v0
	v_mul_f32_e32 v1, v10, v0
	v_add_f32_e32 v0, v11, v1
	v_sub_f32_e32 v2, v0, v11
	v_sub_f32_e32 v13, v1, v2
	v_mul_f32_e32 v1, v0, v0
	v_fma_f32 v3, v0, v0, -v1
	v_add_f32_e32 v2, v13, v13
	v_fmac_f32_e32 v3, v0, v2
	v_add_f32_e32 v2, v1, v3
	v_fmac_f32_e32 v4, 0x3e76c4e1, v2
	v_fmaak_f32 v4, v2, v4, 0x3ecccdef
	v_sub_f32_e32 v1, v2, v1
	v_sub_f32_e32 v14, v3, v1
	v_mul_f32_e32 v1, v2, v4
	v_fma_f32 v3, v2, v4, -v1
	v_fmac_f32_e32 v3, v14, v4
	v_add_f32_e32 v4, v1, v3
	v_add_f32_e32 v5, 0x3f2aaaaa, v4
	v_sub_f32_e32 v1, v4, v1
	v_sub_f32_e32 v1, v3, v1
	v_add_f32_e32 v3, 0xbf2aaaaa, v5
	v_add_f32_e32 v1, 0x31739010, v1
	v_sub_f32_e32 v3, v4, v3
	v_pk_mul_f32 v[8:9], v[0:1], v[2:3]
	v_pk_add_f32 v[10:11], v[0:1], v[2:3]
	v_fma_f32 v4, v2, v0, -v8
	v_fmac_f32_e32 v4, v2, v13
	v_mov_b32_e32 v9, v11
	v_fmac_f32_e32 v4, v14, v0
	v_pk_add_f32 v[2:3], v[8:9], v[4:5]
	v_ldexp_f32 v14, v13, 1
	v_sub_f32_e32 v1, v2, v8
	v_sub_f32_e32 v1, v4, v1
	v_sub_f32_e32 v4, v5, v3
	v_add_f32_e32 v9, v11, v4
	v_pk_mul_f32 v[4:5], v[2:3], v[2:3] op_sel:[0,1] op_sel_hi:[1,0]
	v_cvt_f64_f32_e32 v[10:11], v12
	v_frexp_exp_i32_f64_e32 v5, v[10:11]
	v_subbrev_co_u32_e32 v5, vcc, 0, v5, vcc
	v_cvt_f32_i32_e32 v5, v5
	v_fma_f32 v8, v2, v3, -v4
	v_fmac_f32_e32 v8, v2, v9
	v_fmac_f32_e32 v8, v1, v3
	v_mul_f32_e32 v2, 0x3f317218, v5
	v_fma_f32 v1, v5, s0, -v2
	v_fmamk_f32 v10, v5, 0xb102e308, v1
	v_ldexp_f32 v11, v0, 1
	v_add_f32_e32 v3, v4, v8
	v_pk_add_f32 v[0:1], v[2:3], v[10:11]
	v_mov_b32_e32 v12, v3
	v_mov_b32_e32 v13, v1
	v_mov_b32_e32 v5, v11
	v_pk_add_f32 v[4:5], v[12:13], v[4:5] neg_lo:[0,1] neg_hi:[0,1]
	v_mov_b32_e32 v9, v3
	v_pk_add_f32 v[4:5], v[8:9], v[4:5] neg_lo:[0,1] neg_hi:[0,1]
	v_mov_b32_e32 v11, v0
	v_add_f32_e32 v3, v14, v4
	v_add_f32_e32 v3, v3, v5
	v_pk_add_f32 v[4:5], v[0:1], v[2:3] neg_lo:[0,1] neg_hi:[0,1]
	v_pk_add_f32 v[8:9], v[0:1], v[2:3]
	v_mov_b32_e32 v2, v3
	v_mov_b32_e32 v5, v9
	v_pk_add_f32 v[12:13], v[10:11], v[4:5] neg_lo:[0,1] neg_hi:[0,1]
	v_pk_add_f32 v[4:5], v[10:11], v[4:5]
	v_mov_b32_e32 v3, v0
	v_pk_add_f32 v[10:11], v[4:5], v[0:1] op_sel:[1,0] op_sel_hi:[0,1] neg_lo:[0,1] neg_hi:[0,1]
	v_pk_add_f32 v[14:15], v[8:9], v[10:11] op_sel_hi:[1,0] neg_lo:[0,1] neg_hi:[0,1]
	v_mov_b32_e32 v8, v9
	v_mov_b32_e32 v9, v5
	v_pk_mov_b32 v[10:11], v[0:1], v[10:11] op_sel:[1,0]
	v_mov_b32_e32 v14, v12
	v_pk_add_f32 v[8:9], v[8:9], v[10:11] neg_lo:[0,1] neg_hi:[0,1]
	v_mov_b32_e32 v13, v5
	v_pk_add_f32 v[0:1], v[2:3], v[8:9] neg_lo:[0,1] neg_hi:[0,1]
	s_movk_i32 s0, 0x204
	v_pk_add_f32 v[2:3], v[14:15], v[0:1]
	s_mov_b32 s3, 0x7f800000
	v_pk_add_f32 v[8:9], v[2:3], v[2:3] op_sel:[0,1] op_sel_hi:[1,0]
	s_mov_b64 s[14:15], 0
	v_pk_add_f32 v[4:5], v[4:5], v[8:9] op_sel:[1,0] op_sel_hi:[0,1]
	v_mov_b32_e32 v3, v4
	v_pk_add_f32 v[10:11], v[2:3], v[12:13] neg_lo:[0,1] neg_hi:[0,1]
	v_mov_b32_e32 v1, v8
	v_sub_f32_e32 v2, v2, v10
	v_pk_add_f32 v[0:1], v[0:1], v[10:11] neg_lo:[0,1] neg_hi:[0,1]
	v_sub_f32_e32 v2, v12, v2
	v_add_f32_e32 v0, v0, v2
	v_add_f32_e32 v0, v0, v1
	v_add_f32_e32 v1, v4, v0
	v_sub_f32_e32 v2, v1, v4
	v_sub_f32_e32 v0, v0, v2
	v_mul_f32_e32 v2, v7, v1
	v_fma_f32 v1, v7, v1, -v2
	v_fmac_f32_e32 v1, v7, v0
	v_add_f32_e32 v0, v2, v1
	v_cmp_class_f32_e64 vcc, v2, s0
	v_sub_f32_e32 v3, v0, v2
	v_sub_f32_e32 v1, v1, v3
	v_cndmask_b32_e32 v0, v0, v2, vcc
	v_mov_b32_e32 v2, 0x37000000
	v_cmp_eq_f32_e32 vcc, s1, v0
	s_mov_b32 s18, 0xfe5163ab
	s_mov_b32 s19, 0x3c439041
	v_cndmask_b32_e32 v2, 0, v2, vcc
	v_sub_f32_e32 v3, v0, v2
	v_mul_f32_e32 v4, 0x3fb8aa3b, v3
	v_fma_f32 v5, v3, s2, -v4
	v_rndne_f32_e32 v8, v4
	v_fmamk_f32 v5, v3, 0x32a5705f, v5
	v_sub_f32_e32 v4, v4, v8
	v_add_f32_e32 v4, v4, v5
	v_exp_f32_e32 v4, v4
	v_cvt_i32_f32_e32 v5, v8
	v_cmp_neq_f32_e64 vcc, |v0|, s3
	s_mov_b32 s2, 0xc2ce8ed0
	s_mov_b32 s20, 0xdb629599
	v_cndmask_b32_e32 v0, 0, v1, vcc
	v_ldexp_f32 v1, v4, v5
	v_cmp_ngt_f32_e32 vcc, s2, v3
	v_add_f32_e32 v0, v2, v0
	v_mov_b32_e32 v2, 0x7f800000
	v_cndmask_b32_e32 v1, 0, v1, vcc
	v_cmp_nlt_f32_e32 vcc, s1, v3
	s_lshl_b32 s2, s94, 9
	s_mov_b32 s21, 0xf534ddc0
	v_cndmask_b32_e32 v1, v2, v1, vcc
	v_fma_f32 v0, v1, v0, v1
	v_cmp_class_f32_e64 vcc, v1, s0
	s_mov_b32 s22, 0xfc2757d1
	s_mov_b32 s23, 0x4e441529
	v_cndmask_b32_e32 v0, v0, v1, vcc
	v_and_b32_e32 v1, 0x7fffffff, v0
	v_div_scale_f32 v2, s[0:1], v1, v1, 1.0
	v_rcp_f32_e32 v3, v2
	v_div_scale_f32 v1, vcc, 1.0, v1, 1.0
	s_mov_b64 s[0:1], 0x4300000
	v_fma_f32 v4, -v2, v3, 1.0
	v_fmac_f32_e32 v3, v4, v3
	v_mul_f32_e32 v4, v1, v3
	v_fma_f32 v5, -v2, v4, v1
	v_fmac_f32_e32 v4, v5, v3
	v_fma_f32 v1, -v2, v4, v1
	v_div_fmas_f32 v1, v1, v3, v4
	v_div_fixup_f32 v0, v1, |v0|, 1.0
	v_cmp_neq_f32_e32 vcc, s3, v7
	v_mov_b32_e32 v1, 0
	s_brev_b32 s3, 18
	v_cndmask_b32_e32 v7, 0, v0, vcc
	v_lshlrev_b32_e32 v0, 2, v16
	v_lshl_add_u64 v[2:3], s[90:91], 0, v[0:1]
	v_lshl_add_u64 v[2:3], v[2:3], 0, s[0:1]
	s_mov_b32 s24, 0xa2f9836e
	s_mov_b32 s25, 0x3fc90fda
	s_mov_b32 s26, 0x3f22f983
	s_mov_b32 s27, 0xbfc90fda
	v_mov_b32_e32 v8, 0x3c0881c4
	v_mov_b32_e32 v9, 0xbab64f3b
	s_brev_b32 s28, 1
	s_movk_i32 s29, 0x1f8
	s_mov_b32 s30, 0x3ffff
	v_not_b32_e32 v10, 63
	v_not_b32_e32 v11, 31
	v_mov_b32_e32 v12, 0x7fc00000
	s_branch .LBB0_107

; __device__ __forceinline__ void rows_norm_mod(Ctx& X, const float* src, const bf16_t* delta, float* x1out, const float* w, const float* sc, const float* sh, bf16_t* dst, bool do_cs) {
;     ...
;     if (do_cs) {
;         const int gt = blockIdx.x * 512 + X.tid, NT = X.G * 512;
;         float* cs = (float*)(X.ws + WS_CS);
;         for (int idx = gt; idx < S * 16; idx += NT) {
;             const int rw = idx >> 4, i = idx & 15;
;             const float invf = 1.0f / powf(500000.0f, (float)(2 * i) * (1.0f / 32.0f));
;             const float ang = (float)X.pos[rw] * invf;
;             cs[(size_t)rw * 32 + i] = cosf(ang); cs[(size_t)rw * 32 + 16 + i] = sinf(ang);
;         }
;     }
.LBB0_115:
	s_or_b64 exec, exec, s[12:13]
	s_cmp_eq_u32 s31, 1
	s_cbranch_scc0 .LBB0_116
	s_mov_b32 s31, 2
	s_branch .Lp1_rows
